# MODE1 out-proj epilogue: hoist 16 residual loads, counted vmcnt instead of vmcnt(0) chain
# speedup vs baseline: 1.0451x; 1.0451x over previous
; #define PG8_STAGE(bufoff, gbase, voff) do { _Pragma("unroll") for (int _i = 0; _i < 2; ++_i) \
;         __builtin_amdgcn_global_load_lds((const unsigned*)((const char*)(gbase) + (voff)[_i]), (LAS unsigned*)(lds + (bufoff) + ldsw + _i * 8192), 16, 0, 0); } while (0)
; #define PG8_LDA(dst, b, h) do { _Pragma("unroll") for (int m = 0; m < 4; ++m) _Pragma("unroll") for (int k = 0; k < 2; ++k) dst[m][k] = *(const LAS bf16x8*)(lds + PG8_SA(b, h) + aoff + m * 2048 + k * 1024); } while (0)
; #define PG8_WAIT_V(n) asm volatile("s_waitcnt vmcnt(" #n ")" ::: "memory")
; #define PG8_WAIT_L(n) asm volatile("s_waitcnt lgkmcnt(" #n ")" ::: "memory")
; template <int MODE>
; __device__ __forceinline__ void gemm_phase(LAS unsigned char* lds, const Params& p, int l, int single) {
;     ...
;         for (int t = 0; t < nt; t += 2) {
;             const bool last = (t == nt - 2);
;             const char* a1 = cA + (size_t)(t + 1) * kstep;
;             const char* a2 = last ? nA : cA + (size_t)(t + 2) * kstep; const char* b2 = last ? nB : cB + (size_t)(t + 2) * kstep;
;             const char* a3 = a2 + kstep; const char* b3 = b2 + kstep;
;             PG8_LDB(B0, 0, 0); PG8_SCHED; PG8_LDA(At, 0, 0); PG8_STAGE(PG8_SA(1, 1), a1 + hstep, voffA);
;             PG8_WAIT_L(8); PG8_BAR; PG8_WAIT_L(0); PG8_MMA(0, 0, At, B0); PG8_BAR; PG8_SCHED;
;             PG8_LDB(B1, 0, 1); PG8_STAGE(PG8_SB(0, 0), b2, voffB);
;             PG8_BAR; PG8_WAIT_L(0); PG8_MMA(0, 1, At, B1); PG8_BAR;
;             PG8_LDA(At, 0, 1); PG8_STAGE(PG8_SA(0, 0), a2, voffA);
;             PG8_BAR; PG8_WAIT_L(0); PG8_MMA(1, 0, At, B0); PG8_BAR; PG8_SCHED;
;             PG8_STAGE(PG8_SB(0, 1), b2 + hstep, voffB);
;             PG8_WAIT_V(6); PG8_BAR; PG8_MMA(1, 1, At, B1); PG8_BAR;
;             PG8_LDB(B0, 1, 0); PG8_SCHED; PG8_LDA(At, 1, 0); PG8_STAGE(PG8_SA(0, 1), a2 + hstep, voffA);
;             PG8_WAIT_L(8); PG8_BAR; PG8_WAIT_L(0); PG8_MMA(0, 0, At, B0); PG8_BAR; PG8_SCHED;
;             PG8_LDB(B1, 1, 1); PG8_STAGE(PG8_SB(1, 0), b3, voffB);
;             PG8_BAR; PG8_WAIT_L(0); PG8_MMA(0, 1, At, B1); PG8_BAR;
;             PG8_LDA(At, 1, 1); PG8_STAGE(PG8_SA(1, 0), a3, voffA);
;             PG8_BAR; PG8_WAIT_L(0); PG8_MMA(1, 0, At, B0); PG8_BAR; PG8_SCHED;
;             PG8_STAGE(PG8_SB(1, 1), b3 + hstep, voffB);
;             PG8_WAIT_V(6); PG8_BAR; PG8_MMA(1, 1, At, B1); PG8_BAR;
.LBB0_643:
	s_add_u32 s20, s33, s38
	s_addc_u32 s21, s78, s39
	s_add_u32 s20, s20, 0x2d58c100
	s_addc_u32 s21, s21, 0
	s_add_u32 s90, s79, s38
	s_addc_u32 s93, s84, s39
	s_add_i32 s96, 0, 0x10000
	v_add_u32_e32 v142, s96, v155
	ds_read_b128 v[158:161], v142
	ds_read_b128 v[162:165], v142 offset:1024
	ds_read_b128 v[166:169], v142 offset:2048
	ds_read_b128 v[170:173], v142 offset:3072
	s_cmpk_eq_i32 s38, 0xf00
	s_cselect_b32 s41, s19, s21
	s_cselect_b32 s40, s18, s20
	s_cselect_b32 s21, s17, s93
	s_cselect_b32 s20, s16, s90
	v_lshl_add_u64 v[142:143], v[150:151], 0, s[38:39]
	s_add_i32 m0, s7, 0xc000
	ds_read_b128 v[174:177], v156
	ds_read_b128 v[178:181], v156 offset:1024
	ds_read_b128 v[182:185], v156 offset:2048
	ds_read_b128 v[186:189], v156 offset:3072
	ds_read_b128 v[190:193], v156 offset:4096
	ds_read_b128 v[194:197], v156 offset:5120
	ds_read_b128 v[208:211], v156 offset:6144
	ds_read_b128 v[212:215], v156 offset:7168
	global_load_lds_dwordx4 v[142:143], off
	v_lshl_add_u64 v[142:143], v[152:153], 0, s[38:39]
	s_add_i32 m0, s7, 0xe000
	s_nop 0
	global_load_lds_dwordx4 v[142:143], off
	s_waitcnt lgkmcnt(8)
	s_barrier
	s_waitcnt lgkmcnt(0)
	s_setprio 1
	s_waitcnt lgkmcnt(0)
	v_mfma_f32_16x16x32_bf16 v[126:129], v[158:161], v[174:177], v[126:129]
	v_mfma_f32_16x16x32_bf16 v[122:125], v[166:169], v[174:177], v[122:125]
	v_mfma_f32_16x16x32_bf16 v[110:113], v[158:161], v[182:185], v[110:113]
	v_mfma_f32_16x16x32_bf16 v[106:109], v[166:169], v[182:185], v[106:109]
	v_mfma_f32_16x16x32_bf16 v[94:97], v[158:161], v[190:193], v[94:97]
	v_mfma_f32_16x16x32_bf16 v[90:93], v[166:169], v[190:193], v[90:93]
	v_mfma_f32_16x16x32_bf16 v[78:81], v[158:161], v[208:211], v[78:81]
	v_mfma_f32_16x16x32_bf16 v[74:77], v[166:169], v[208:211], v[74:77]
	v_mfma_f32_16x16x32_bf16 v[126:129], v[162:165], v[178:181], v[126:129]
	v_mfma_f32_16x16x32_bf16 v[122:125], v[170:173], v[178:181], v[122:125]
	v_mfma_f32_16x16x32_bf16 v[110:113], v[162:165], v[186:189], v[110:113]
	v_mfma_f32_16x16x32_bf16 v[106:109], v[170:173], v[186:189], v[106:109]
	v_mfma_f32_16x16x32_bf16 v[94:97], v[162:165], v[194:197], v[94:97]
	v_mfma_f32_16x16x32_bf16 v[90:93], v[170:173], v[194:197], v[90:93]
	v_mfma_f32_16x16x32_bf16 v[78:81], v[162:165], v[212:215], v[78:81]
	v_mfma_f32_16x16x32_bf16 v[74:77], v[170:173], v[212:215], v[74:77]
	s_setprio 0
	s_barrier
	s_add_i32 s90, 0, 0x14000
	v_add_u32_e32 v142, s90, v155
	s_add_i32 s93, s96, s2
	ds_read_b128 v[216:219], v142
	ds_read_b128 v[220:223], v142 offset:1024
	ds_read_b128 v[224:227], v142 offset:2048
	ds_read_b128 v[228:231], v142 offset:3072
	v_lshl_add_u64 v[142:143], s[20:21], 0, v[0:1]
	s_mov_b32 m0, s93
	v_lshl_add_u64 v[198:199], s[20:21], 0, v[146:147]
	global_load_lds_dwordx4 v[142:143], off
	s_add_i32 m0, s93, 0x2000
	s_nop 0
	global_load_lds_dwordx4 v[198:199], off
	s_barrier
	s_waitcnt lgkmcnt(0)
	s_setprio 1
	s_waitcnt lgkmcnt(0)
	v_mfma_f32_16x16x32_bf16 v[118:121], v[216:219], v[174:177], v[118:121]
	v_mfma_f32_16x16x32_bf16 v[114:117], v[224:227], v[174:177], v[114:117]
	v_mfma_f32_16x16x32_bf16 v[102:105], v[216:219], v[182:185], v[102:105]
	v_mfma_f32_16x16x32_bf16 v[98:101], v[224:227], v[182:185], v[98:101]
	v_mfma_f32_16x16x32_bf16 v[86:89], v[216:219], v[190:193], v[86:89]
	v_mfma_f32_16x16x32_bf16 v[82:85], v[224:227], v[190:193], v[82:85]
	v_mfma_f32_16x16x32_bf16 v[70:73], v[216:219], v[208:211], v[70:73]
	v_mfma_f32_16x16x32_bf16 v[66:69], v[224:227], v[208:211], v[66:69]
	v_mfma_f32_16x16x32_bf16 v[118:121], v[220:223], v[178:181], v[118:121]
	v_mfma_f32_16x16x32_bf16 v[114:117], v[228:231], v[178:181], v[114:117]
	v_mfma_f32_16x16x32_bf16 v[102:105], v[220:223], v[186:189], v[102:105]
	v_mfma_f32_16x16x32_bf16 v[98:101], v[228:231], v[186:189], v[98:101]
	v_mfma_f32_16x16x32_bf16 v[86:89], v[220:223], v[194:197], v[86:89]
	v_mfma_f32_16x16x32_bf16 v[82:85], v[228:231], v[194:197], v[82:85]
	v_mfma_f32_16x16x32_bf16 v[70:73], v[220:223], v[212:215], v[70:73]
	v_mfma_f32_16x16x32_bf16 v[66:69], v[228:231], v[212:215], v[66:69]
	s_setprio 0
	s_mov_b32 m0, s7
	v_lshl_add_u64 v[232:233], s[40:41], 0, v[130:131]
	s_barrier
	ds_read_b128 v[174:177], v156 offset:16384
	ds_read_b128 v[178:181], v156 offset:17408
	ds_read_b128 v[182:185], v156 offset:18432
	ds_read_b128 v[186:189], v156 offset:19456
	ds_read_b128 v[190:193], v156 offset:20480
	ds_read_b128 v[194:197], v156 offset:21504
	ds_read_b128 v[208:211], v156 offset:22528
	ds_read_b128 v[212:215], v156 offset:23552
	global_load_lds_dwordx4 v[232:233], off
	v_lshl_add_u64 v[234:235], s[40:41], 0, v[132:133]
	s_mov_b32 m0, s10
	s_nop 0
	global_load_lds_dwordx4 v[234:235], off
	s_barrier
	s_waitcnt lgkmcnt(0)
	s_setprio 1
	s_waitcnt lgkmcnt(0)
	v_mfma_f32_16x16x32_bf16 v[62:65], v[158:161], v[174:177], v[62:65]
	v_mfma_f32_16x16x32_bf16 v[58:61], v[166:169], v[174:177], v[58:61]
	v_mfma_f32_16x16x32_bf16 v[46:49], v[158:161], v[182:185], v[46:49]
	v_mfma_f32_16x16x32_bf16 v[42:45], v[166:169], v[182:185], v[42:45]
	v_mfma_f32_16x16x32_bf16 v[30:33], v[158:161], v[190:193], v[30:33]
	v_mfma_f32_16x16x32_bf16 v[26:29], v[166:169], v[190:193], v[26:29]
	v_mfma_f32_16x16x32_bf16 v[14:17], v[158:161], v[208:211], v[14:17]
	v_mfma_f32_16x16x32_bf16 v[10:13], v[166:169], v[208:211], v[10:13]
	v_mfma_f32_16x16x32_bf16 v[62:65], v[162:165], v[178:181], v[62:65]
	v_mfma_f32_16x16x32_bf16 v[58:61], v[170:173], v[178:181], v[58:61]
	v_mfma_f32_16x16x32_bf16 v[46:49], v[162:165], v[186:189], v[46:49]
	v_mfma_f32_16x16x32_bf16 v[42:45], v[170:173], v[186:189], v[42:45]
	v_mfma_f32_16x16x32_bf16 v[30:33], v[162:165], v[194:197], v[30:33]
	v_mfma_f32_16x16x32_bf16 v[26:29], v[170:173], v[194:197], v[26:29]
	v_mfma_f32_16x16x32_bf16 v[14:17], v[162:165], v[212:215], v[14:17]
	v_mfma_f32_16x16x32_bf16 v[10:13], v[170:173], v[212:215], v[10:13]
	s_setprio 0
	s_barrier
; #define PG8_STAGE(bufoff, gbase, voff) do { _Pragma("unroll") for (int _i = 0; _i < 2; ++_i) \
;         __builtin_amdgcn_global_load_lds((const unsigned*)((const char*)(gbase) + (voff)[_i]), (LAS unsigned*)(lds + (bufoff) + ldsw + _i * 8192), 16, 0, 0); } while (0)
; #define PG8_LDA(dst, b, h) do { _Pragma("unroll") for (int m = 0; m < 4; ++m) _Pragma("unroll") for (int k = 0; k < 2; ++k) dst[m][k] = *(const LAS bf16x8*)(lds + PG8_SA(b, h) + aoff + m * 2048 + k * 1024); } while (0)
; #define PG8_LDB(dst, b, h) do { _Pragma("unroll") for (int n = 0; n < 2; ++n) _Pragma("unroll") for (int k = 0; k < 2; ++k) dst[n][k] = *(const LAS bf16x8*)(lds + PG8_SB(b, h) + boff + n * 2048 + k * 1024); } while (0)
; #define PG8_WAIT_V(n) asm volatile("s_waitcnt vmcnt(" #n ")" ::: "memory")
; #define PG8_WAIT_L(n) asm volatile("s_waitcnt lgkmcnt(" #n ")" ::: "memory")
; #define PG8_BAR __builtin_amdgcn_s_barrier()
; #define PG8_SCHED __builtin_amdgcn_sched_barrier(0)
; template <int MODE>
; __device__ __forceinline__ void gemm_phase(LAS unsigned char* lds, const Params& p, int l, int single) {
;     ...
;             PG8_LDB(B0, 0, 0); PG8_SCHED; PG8_LDA(At, 0, 0); PG8_STAGE(PG8_SA(1, 1), a1 + hstep, voffA);
;             PG8_WAIT_L(8); PG8_BAR; PG8_WAIT_L(0); PG8_MMA(0, 0, At, B0); PG8_BAR; PG8_SCHED;
;             PG8_LDB(B1, 0, 1); PG8_STAGE(PG8_SB(0, 0), b2, voffB);
;             PG8_BAR; PG8_WAIT_L(0); PG8_MMA(0, 1, At, B1); PG8_BAR;
;             PG8_LDA(At, 0, 1); PG8_STAGE(PG8_SA(0, 0), a2, voffA);
;             PG8_BAR; PG8_WAIT_L(0); PG8_MMA(1, 0, At, B0); PG8_BAR; PG8_SCHED;
;             PG8_STAGE(PG8_SB(0, 1), b2 + hstep, voffB);
;             PG8_WAIT_V(6); PG8_BAR; PG8_MMA(1, 1, At, B1); PG8_BAR;
;             PG8_LDB(B0, 1, 0); PG8_SCHED; PG8_LDA(At, 1, 0); PG8_STAGE(PG8_SA(0, 1), a2 + hstep, voffA);
;             PG8_WAIT_L(8); PG8_BAR; PG8_WAIT_L(0); PG8_MMA(0, 0, At, B0); PG8_BAR; PG8_SCHED;
;             PG8_LDB(B1, 1, 1); PG8_STAGE(PG8_SB(1, 0), b3, voffB);
;             PG8_BAR; PG8_WAIT_L(0); PG8_MMA(0, 1, At, B1); PG8_BAR;
;             PG8_LDA(At, 1, 1); PG8_STAGE(PG8_SA(1, 0), a3, voffA);
;             PG8_BAR; PG8_WAIT_L(0); PG8_MMA(1, 0, At, B0); PG8_BAR; PG8_SCHED;
;             PG8_STAGE(PG8_SB(1, 1), b3 + hstep, voffB);
;             PG8_WAIT_V(6); PG8_BAR; PG8_MMA(1, 1, At, B1); PG8_BAR;
	s_add_u32 s96, s20, 0x80000
	s_addc_u32 s97, s21, 0
	s_add_i32 s90, s90, s2
	v_lshl_add_u64 v[158:159], s[96:97], 0, v[0:1]
	s_mov_b32 m0, s90
	s_nop 0
	global_load_lds_dwordx4 v[158:159], off
	v_lshl_add_u64 v[158:159], s[96:97], 0, v[146:147]
	s_add_i32 m0, s90, 0x2000
	s_nop 0
	global_load_lds_dwordx4 v[158:159], off
	s_waitcnt vmcnt(6)
	s_barrier
	s_setprio 1
	v_mfma_f32_16x16x32_bf16 v[54:57], v[216:219], v[174:177], v[54:57]
	v_mfma_f32_16x16x32_bf16 v[50:53], v[224:227], v[174:177], v[50:53]
	v_mfma_f32_16x16x32_bf16 v[38:41], v[216:219], v[182:185], v[38:41]
	v_mfma_f32_16x16x32_bf16 v[34:37], v[224:227], v[182:185], v[34:37]
	v_mfma_f32_16x16x32_bf16 v[22:25], v[216:219], v[190:193], v[22:25]
	v_mfma_f32_16x16x32_bf16 v[18:21], v[224:227], v[190:193], v[18:21]
	v_mfma_f32_16x16x32_bf16 v[6:9], v[216:219], v[208:211], v[6:9]
	v_mfma_f32_16x16x32_bf16 v[2:5], v[224:227], v[208:211], v[2:5]
	v_mfma_f32_16x16x32_bf16 v[54:57], v[220:223], v[178:181], v[54:57]
	v_mfma_f32_16x16x32_bf16 v[50:53], v[228:231], v[178:181], v[50:53]
	v_mfma_f32_16x16x32_bf16 v[38:41], v[220:223], v[186:189], v[38:41]
	v_mfma_f32_16x16x32_bf16 v[34:37], v[228:231], v[186:189], v[34:37]
	v_mfma_f32_16x16x32_bf16 v[22:25], v[220:223], v[194:197], v[22:25]
	v_mfma_f32_16x16x32_bf16 v[18:21], v[228:231], v[194:197], v[18:21]
	v_mfma_f32_16x16x32_bf16 v[6:9], v[220:223], v[212:215], v[6:9]
	v_mfma_f32_16x16x32_bf16 v[2:5], v[228:231], v[212:215], v[2:5]
	s_setprio 0
	s_add_i32 s90, 0, 0x18000
	v_add_u32_e32 v157, s90, v155
	s_barrier
	ds_read_b128 v[158:161], v157
	ds_read_b128 v[162:165], v157 offset:1024
	ds_read_b128 v[166:169], v157 offset:2048
	ds_read_b128 v[170:173], v157 offset:3072
	s_add_u32 s40, s40, 0x80000
	s_addc_u32 s41, s41, 0
	s_mov_b32 m0, s24
	v_lshl_add_u64 v[216:217], s[40:41], 0, v[130:131]
	ds_read_b128 v[174:177], v156 offset:32768
	ds_read_b128 v[178:181], v156 offset:33792
	ds_read_b128 v[182:185], v156 offset:34816
	ds_read_b128 v[186:189], v156 offset:35840
	ds_read_b128 v[190:193], v156 offset:36864
	ds_read_b128 v[194:197], v156 offset:37888
	ds_read_b128 v[208:211], v156 offset:38912
	ds_read_b128 v[212:215], v156 offset:39936
	global_load_lds_dwordx4 v[216:217], off
	v_lshl_add_u64 v[216:217], s[40:41], 0, v[132:133]
	s_mov_b32 m0, s25
	s_nop 0
	global_load_lds_dwordx4 v[216:217], off
	s_waitcnt lgkmcnt(8)
	s_barrier
	s_waitcnt lgkmcnt(0)
	s_setprio 1
	s_waitcnt lgkmcnt(0)
	v_mfma_f32_16x16x32_bf16 v[126:129], v[158:161], v[174:177], v[126:129]
	v_mfma_f32_16x16x32_bf16 v[122:125], v[166:169], v[174:177], v[122:125]
	v_mfma_f32_16x16x32_bf16 v[110:113], v[158:161], v[182:185], v[110:113]
	v_mfma_f32_16x16x32_bf16 v[106:109], v[166:169], v[182:185], v[106:109]
	v_mfma_f32_16x16x32_bf16 v[94:97], v[158:161], v[190:193], v[94:97]
	v_mfma_f32_16x16x32_bf16 v[90:93], v[166:169], v[190:193], v[90:93]
	v_mfma_f32_16x16x32_bf16 v[78:81], v[158:161], v[208:211], v[78:81]
	v_mfma_f32_16x16x32_bf16 v[74:77], v[166:169], v[208:211], v[74:77]
	v_mfma_f32_16x16x32_bf16 v[126:129], v[162:165], v[178:181], v[126:129]
	v_mfma_f32_16x16x32_bf16 v[122:125], v[170:173], v[178:181], v[122:125]
	v_mfma_f32_16x16x32_bf16 v[110:113], v[162:165], v[186:189], v[110:113]
	v_mfma_f32_16x16x32_bf16 v[106:109], v[170:173], v[186:189], v[106:109]
	v_mfma_f32_16x16x32_bf16 v[94:97], v[162:165], v[194:197], v[94:97]
	v_mfma_f32_16x16x32_bf16 v[90:93], v[170:173], v[194:197], v[90:93]
	v_mfma_f32_16x16x32_bf16 v[78:81], v[162:165], v[212:215], v[78:81]
	v_mfma_f32_16x16x32_bf16 v[74:77], v[170:173], v[212:215], v[74:77]
	s_setprio 0
	s_barrier
	s_add_i32 s40, 0, 0x1c000
	s_add_i32 s41, s90, s2
	v_add_u32_e32 v157, s40, v155
	v_lshl_add_u64 v[142:143], v[142:143], 0, s[94:95]
	s_mov_b32 m0, s41
	ds_read_b128 v[216:219], v157
	ds_read_b128 v[220:223], v157 offset:1024
	ds_read_b128 v[224:227], v157 offset:2048
	ds_read_b128 v[228:231], v157 offset:3072
	global_load_lds_dwordx4 v[142:143], off
	v_lshl_add_u64 v[142:143], v[198:199], 0, s[94:95]
	s_add_i32 m0, s41, 0x2000
	s_nop 0
	global_load_lds_dwordx4 v[142:143], off
	s_barrier
	s_waitcnt lgkmcnt(0)
	s_setprio 1
	s_waitcnt lgkmcnt(0)
	v_mfma_f32_16x16x32_bf16 v[118:121], v[216:219], v[174:177], v[118:121]
	v_mfma_f32_16x16x32_bf16 v[114:117], v[224:227], v[174:177], v[114:117]
	v_mfma_f32_16x16x32_bf16 v[102:105], v[216:219], v[182:185], v[102:105]
	v_mfma_f32_16x16x32_bf16 v[98:101], v[224:227], v[182:185], v[98:101]
	v_mfma_f32_16x16x32_bf16 v[86:89], v[216:219], v[190:193], v[86:89]
	v_mfma_f32_16x16x32_bf16 v[82:85], v[224:227], v[190:193], v[82:85]
	v_mfma_f32_16x16x32_bf16 v[70:73], v[216:219], v[208:211], v[70:73]
	v_mfma_f32_16x16x32_bf16 v[66:69], v[224:227], v[208:211], v[66:69]
	v_mfma_f32_16x16x32_bf16 v[118:121], v[220:223], v[178:181], v[118:121]
	v_mfma_f32_16x16x32_bf16 v[114:117], v[228:231], v[178:181], v[114:117]
	v_mfma_f32_16x16x32_bf16 v[102:105], v[220:223], v[186:189], v[102:105]
	v_mfma_f32_16x16x32_bf16 v[98:101], v[228:231], v[186:189], v[98:101]
	v_mfma_f32_16x16x32_bf16 v[86:89], v[220:223], v[194:197], v[86:89]
	v_mfma_f32_16x16x32_bf16 v[82:85], v[228:231], v[194:197], v[82:85]
	v_mfma_f32_16x16x32_bf16 v[70:73], v[220:223], v[212:215], v[70:73]
	v_mfma_f32_16x16x32_bf16 v[66:69], v[228:231], v[212:215], v[66:69]
	s_setprio 0
	s_mov_b32 m0, s28
	v_lshl_add_u64 v[142:143], v[232:233], 0, s[94:95]
	s_barrier
	ds_read_b128 v[174:177], v156 offset:49152
	ds_read_b128 v[178:181], v156 offset:50176
	ds_read_b128 v[182:185], v156 offset:51200
	ds_read_b128 v[186:189], v156 offset:52224
	ds_read_b128 v[190:193], v156 offset:53248
	ds_read_b128 v[194:197], v156 offset:54272
	ds_read_b128 v[208:211], v156 offset:55296
	ds_read_b128 v[212:215], v156 offset:56320
	global_load_lds_dwordx4 v[142:143], off
	v_lshl_add_u64 v[142:143], v[234:235], 0, s[94:95]
	s_mov_b32 m0, s29
	s_nop 0
	global_load_lds_dwordx4 v[142:143], off
	s_barrier
; __device__ __forceinline__ float bflo(unsigned w) { return __uint_as_float(w << 16); }
; __device__ __forceinline__ float bfhi(unsigned w) { return __uint_as_float(w & 0xffff0000u); }
; #define PG8_STAGE(bufoff, gbase, voff) do { _Pragma("unroll") for (int _i = 0; _i < 2; ++_i) \
;         __builtin_amdgcn_global_load_lds((const unsigned*)((const char*)(gbase) + (voff)[_i]), (LAS unsigned*)(lds + (bufoff) + ldsw + _i * 8192), 16, 0, 0); } while (0)
; #define PG8_MMA(ai, bj, At, Bt) do { __builtin_amdgcn_s_setprio(1); _Pragma("unroll") for (int m = 0; m < 4; ++m) _Pragma("unroll") for (int n = 0; n < 2; ++n) _Pragma("unroll") for (int k = 0; k < 2; ++k) \
;         acc[ai][bj][m][n] = __builtin_amdgcn_mfma_f32_16x16x32_bf16(Bt[n][k], At[m][k], acc[ai][bj][m][n], 0, 0, 0); __builtin_amdgcn_s_setprio(0); } while (0)
; #define PG8_WAIT_V(n) asm volatile("s_waitcnt vmcnt(" #n ")" ::: "memory")
; template <int MODE>
; __device__ __forceinline__ void gemm_epilogue(const Params& p, int l, const f32x4 (&acc)[2][2][4][2], const Unit& u, int wr, int wc, int fr, int fq, const LAS float* rl, int pm0) {
;     ...
;         u16* xb = (u16*)(ws + WS_XB);
;         u64* ssn = (u64*)(ws + WS_SUMSQ) + (size_t)(l + 1) * T;
; #pragma unroll
;         for (int ai = 0; ai < 2; ++ai)
; #pragma unroll
;             for (int m = 0; m < 4; ++m) {
;                 const int tok = u.pm * 256 + 128 * ai + 64 * wr + 16 * m + fr;
;                 float part = 0.f;
; #pragma unroll
;                 for (int bj = 0; bj < 2; ++bj) {
;                     const size_t idx = (size_t)tok * 2048 + u.pn * 256 + 128 * bj + 32 * wc + 8 * fq;
;                     const u32x4 xw = *(const u32x4*)(xb + idx);
;                     f32x4 y0 = (f32x4){bflo(xw.x), bfhi(xw.x), bflo(xw.y), bfhi(xw.y)}, y1 = (f32x4){bflo(xw.z), bfhi(xw.z), bflo(xw.w), bfhi(xw.w)};
;                     y0 += acc[ai][bj][m][0]; y1 += acc[ai][bj][m][1];
; template <int MODE>
; __device__ __forceinline__ void gemm_phase(LAS unsigned char* lds, const Params& p, int l, int single) {
;     ...
;             PG8_BAR; PG8_WAIT_L(0); PG8_MMA(1, 0, At, B0); PG8_BAR; PG8_SCHED;
;             PG8_STAGE(PG8_SB(1, 1), b3 + hstep, voffB);
;             PG8_WAIT_V(6); PG8_BAR; PG8_MMA(1, 1, At, B1); PG8_BAR;
;         }
;         gemm_epilogue<MODE>(p, l, acc, cur, wr, wc, fr, fq, rl, pm0);
;         if (!has_next) break;
	s_waitcnt lgkmcnt(0)
	s_setprio 1
	s_waitcnt lgkmcnt(0)
	v_mfma_f32_16x16x32_bf16 v[62:65], v[158:161], v[174:177], v[62:65]
	v_mfma_f32_16x16x32_bf16 v[58:61], v[166:169], v[174:177], v[58:61]
	v_mfma_f32_16x16x32_bf16 v[46:49], v[158:161], v[182:185], v[46:49]
	v_mfma_f32_16x16x32_bf16 v[42:45], v[166:169], v[182:185], v[42:45]
	v_mfma_f32_16x16x32_bf16 v[30:33], v[158:161], v[190:193], v[30:33]
	v_mfma_f32_16x16x32_bf16 v[26:29], v[166:169], v[190:193], v[26:29]
	v_mfma_f32_16x16x32_bf16 v[14:17], v[158:161], v[208:211], v[14:17]
	v_mfma_f32_16x16x32_bf16 v[10:13], v[166:169], v[208:211], v[10:13]
	v_mfma_f32_16x16x32_bf16 v[62:65], v[162:165], v[178:181], v[62:65]
	v_mfma_f32_16x16x32_bf16 v[58:61], v[170:173], v[178:181], v[58:61]
	v_mfma_f32_16x16x32_bf16 v[46:49], v[162:165], v[186:189], v[46:49]
	v_mfma_f32_16x16x32_bf16 v[42:45], v[170:173], v[186:189], v[42:45]
	v_mfma_f32_16x16x32_bf16 v[30:33], v[162:165], v[194:197], v[30:33]
	v_mfma_f32_16x16x32_bf16 v[26:29], v[170:173], v[194:197], v[26:29]
	v_mfma_f32_16x16x32_bf16 v[14:17], v[162:165], v[212:215], v[14:17]
	v_mfma_f32_16x16x32_bf16 v[10:13], v[170:173], v[212:215], v[10:13]
	s_setprio 0
	s_barrier
	s_add_u32 s20, s20, 0x80080
	s_addc_u32 s21, s21, 0
	s_add_i32 s40, s40, s2
	v_lshl_add_u64 v[142:143], s[20:21], 0, v[0:1]
	s_mov_b32 m0, s40
	s_nop 0
	global_load_lds_dwordx4 v[142:143], off
	v_lshl_add_u64 v[142:143], s[20:21], 0, v[146:147]
	s_add_i32 m0, s40, 0x2000
	s_nop 0
	global_load_lds_dwordx4 v[142:143], off
	s_waitcnt vmcnt(6)
	s_barrier
	s_setprio 1
	v_mfma_f32_16x16x32_bf16 v[54:57], v[216:219], v[174:177], v[54:57]
	v_mfma_f32_16x16x32_bf16 v[50:53], v[224:227], v[174:177], v[50:53]
	v_mfma_f32_16x16x32_bf16 v[38:41], v[216:219], v[182:185], v[38:41]
	v_mfma_f32_16x16x32_bf16 v[34:37], v[224:227], v[182:185], v[34:37]
	v_mfma_f32_16x16x32_bf16 v[22:25], v[216:219], v[190:193], v[22:25]
	v_mfma_f32_16x16x32_bf16 v[18:21], v[224:227], v[190:193], v[18:21]
	v_mfma_f32_16x16x32_bf16 v[6:9], v[216:219], v[208:211], v[6:9]
	v_mfma_f32_16x16x32_bf16 v[2:5], v[224:227], v[208:211], v[2:5]
	v_mfma_f32_16x16x32_bf16 v[54:57], v[220:223], v[178:181], v[54:57]
	v_mfma_f32_16x16x32_bf16 v[50:53], v[228:231], v[178:181], v[50:53]
	v_mfma_f32_16x16x32_bf16 v[38:41], v[220:223], v[186:189], v[38:41]
	v_mfma_f32_16x16x32_bf16 v[34:37], v[228:231], v[186:189], v[34:37]
	v_mfma_f32_16x16x32_bf16 v[22:25], v[220:223], v[194:197], v[22:25]
	v_mfma_f32_16x16x32_bf16 v[18:21], v[228:231], v[194:197], v[18:21]
	v_mfma_f32_16x16x32_bf16 v[6:9], v[220:223], v[212:215], v[6:9]
	v_mfma_f32_16x16x32_bf16 v[2:5], v[228:231], v[212:215], v[2:5]
	s_setprio 0
	s_add_i32 s85, s85, 2
	s_add_u32 s38, s38, 0x100
	s_addc_u32 s39, s39, 0
	s_cmp_gt_u32 s85, 29
	s_barrier
	s_cbranch_scc0 .LBB0_643
	s_add_i32 s0, s0, 1
	s_mul_hi_i32 s2, s0, 0x21000
	s_mul_i32 s0, s0, 0x21000
	s_add_u32 s16, s80, s0
	s_addc_u32 s17, s81, s2
	s_lshl_b32 s2, s1, 8
	s_lshl_b32 s0, s1, 9
	s_add_u32 s0, s52, s0
	s_addc_u32 s1, s53, 0
	s_lshl_b32 s7, s11, 1
	v_lshl_add_u32 v130, s76, 8, v149
	s_add_u32 s0, s0, s7
	s_addc_u32 s1, s1, 0
	v_mov_b32_e32 v149, v1
	v_ashrrev_i32_e32 v131, 31, v130
	v_lshl_add_u64 v[132:133], s[0:1], 0, v[148:149]
	v_mov_b32_e32 v162, v130
	v_ashrrev_i32_e32 v163, 31, v162
	v_lshlrev_b64 v[162:163], 12, v[162:163]
	v_lshl_add_u64 v[162:163], v[132:133], 0, v[162:163]
	global_load_dwordx4 v[158:161], v[162:163], off
	global_load_dwordx4 v[162:165], v[162:163], off offset:256
	v_add_u32_e32 v170, 0x10, v130
	v_ashrrev_i32_e32 v171, 31, v170
	v_lshlrev_b64 v[170:171], 12, v[170:171]
	v_lshl_add_u64 v[170:171], v[132:133], 0, v[170:171]
	global_load_dwordx4 v[166:169], v[170:171], off
	global_load_dwordx4 v[170:173], v[170:171], off offset:256
	v_add_u32_e32 v178, 0x20, v130
	v_ashrrev_i32_e32 v179, 31, v178
	v_lshlrev_b64 v[178:179], 12, v[178:179]
	v_lshl_add_u64 v[178:179], v[132:133], 0, v[178:179]
	global_load_dwordx4 v[174:177], v[178:179], off
	global_load_dwordx4 v[178:181], v[178:179], off offset:256
	v_add_u32_e32 v186, 0x30, v130
	v_ashrrev_i32_e32 v187, 31, v186
	v_lshlrev_b64 v[186:187], 12, v[186:187]
	v_lshl_add_u64 v[186:187], v[132:133], 0, v[186:187]
	global_load_dwordx4 v[182:185], v[186:187], off
	global_load_dwordx4 v[186:189], v[186:187], off offset:256
	v_add_u32_e32 v194, 0x80, v130
	v_ashrrev_i32_e32 v195, 31, v194
	v_lshlrev_b64 v[194:195], 12, v[194:195]
	v_lshl_add_u64 v[194:195], v[132:133], 0, v[194:195]
	global_load_dwordx4 v[190:193], v[194:195], off
	global_load_dwordx4 v[194:197], v[194:195], off offset:256
	v_add_u32_e32 v212, 0x90, v130
	v_ashrrev_i32_e32 v213, 31, v212
	v_lshlrev_b64 v[212:213], 12, v[212:213]
	v_lshl_add_u64 v[212:213], v[132:133], 0, v[212:213]
	global_load_dwordx4 v[208:211], v[212:213], off
	global_load_dwordx4 v[212:215], v[212:213], off offset:256
	v_add_u32_e32 v220, 0xa0, v130
	v_ashrrev_i32_e32 v221, 31, v220
	v_lshlrev_b64 v[220:221], 12, v[220:221]
	v_lshl_add_u64 v[220:221], v[132:133], 0, v[220:221]
	global_load_dwordx4 v[216:219], v[220:221], off
	global_load_dwordx4 v[220:223], v[220:221], off offset:256
	v_add_u32_e32 v228, 0xb0, v130
	v_ashrrev_i32_e32 v229, 31, v228
	v_lshlrev_b64 v[228:229], 12, v[228:229]
	v_lshl_add_u64 v[228:229], v[132:133], 0, v[228:229]
	global_load_dwordx4 v[224:227], v[228:229], off
	global_load_dwordx4 v[228:231], v[228:229], off offset:256
	v_lshlrev_b64 v[142:143], 12, v[130:131]
	v_lshl_add_u64 v[152:153], v[132:133], 0, v[142:143]
	v_lshl_or_b32 v0, v154, 3, s2
	v_or_b32_e32 v0, s11, v0
	v_add_u32_e32 v146, 0x10800000, v142
	v_lshlrev_b32_e32 v0, 1, v0
	v_or_b32_e32 v147, v146, v0
	v_cmp_eq_u32_e32 vcc, 0, v154
	s_waitcnt vmcnt(15)
; __device__ __forceinline__ unsigned cvt_pk_bf16(float lo, float hi) { unsigned r; asm("v_cvt_pk_bf16_f32 %0, %1, %2" : "=v"(r) : "v"(lo), "v"(hi)); return r; }
; __device__ __forceinline__ float bflo(unsigned w) { return __uint_as_float(w << 16); }
; __device__ __forceinline__ float bfhi(unsigned w) { return __uint_as_float(w & 0xffff0000u); }
; #define WT_STORE16(ptr, val) __builtin_amdgcn_raw_buffer_store_b128((val), wsr, (int)((const char*)(ptr) - (const char*)ws), 0, 16)
; template <int MODE>
; __device__ __forceinline__ void gemm_epilogue(const Params& p, int l, const f32x4 (&acc)[2][2][4][2], const Unit& u, int wr, int wc, int fr, int fq, const LAS float* rl, int pm0) {
;     ...
; #pragma unroll
;         for (int ai = 0; ai < 2; ++ai)
; #pragma unroll
;             for (int m = 0; m < 4; ++m) {
;                 const int tok = u.pm * 256 + 128 * ai + 64 * wr + 16 * m + fr;
;                 float part = 0.f;
; #pragma unroll
;                 for (int bj = 0; bj < 2; ++bj) {
;                     const size_t idx = (size_t)tok * 2048 + u.pn * 256 + 128 * bj + 32 * wc + 8 * fq;
;                     const u32x4 xw = *(const u32x4*)(xb + idx);
;                     f32x4 y0 = (f32x4){bflo(xw.x), bfhi(xw.x), bflo(xw.y), bfhi(xw.y)}, y1 = (f32x4){bflo(xw.z), bfhi(xw.z), bflo(xw.w), bfhi(xw.w)};
;                     y0 += acc[ai][bj][m][0]; y1 += acc[ai][bj][m][1];
;                     part += y0[0] * y0[0] + y0[1] * y0[1] + y0[2] * y0[2] + y0[3] * y0[3] + y1[0] * y1[0] + y1[1] * y1[1] + y1[2] * y1[2] + y1[3] * y1[3];
;                     u32x4 w; w.x = cvt_pk_bf16(y0[0], y0[1]); w.y = cvt_pk_bf16(y0[2], y0[3]); w.z = cvt_pk_bf16(y1[0], y1[1]); w.w = cvt_pk_bf16(y1[2], y1[3]);
;                     WT_STORE16(xb + idx, w);
;                 }
;                 part += __shfl_xor(part, 16); part += __shfl_xor(part, 32);
;                 if (fq == 0) atomicAdd(ssn + tok, (u64)(part * SS_SCALE));
;             }
	v_mov_b32_e32 v148, v158
	v_mov_b32_e32 v149, v159
	v_mov_b32_e32 v150, v160
	v_mov_b32_e32 v151, v161
	v_lshlrev_b32_e32 v142, 16, v148
	v_and_b32_e32 v143, 0xffff0000, v148
	v_lshlrev_b32_e32 v148, 16, v149
	v_and_b32_e32 v149, 0xffff0000, v149
	v_lshlrev_b32_e32 v156, 16, v150
	v_and_b32_e32 v157, 0xffff0000, v150
	v_lshlrev_b32_e32 v150, 16, v151
	v_and_b32_e32 v151, 0xffff0000, v151
	v_pk_add_f32 v[128:129], v[128:129], v[148:149]
	v_pk_add_f32 v[142:143], v[126:127], v[142:143]
	v_pk_add_f32 v[124:125], v[124:125], v[150:151]
	v_pk_add_f32 v[122:123], v[122:123], v[156:157]
	v_cvt_pk_bf16_f32 v148, v142, v143
	v_cvt_pk_bf16_f32 v149, v128, v129
	v_cvt_pk_bf16_f32 v151, v124, v125
	v_and_b32_e32 v127, 64, v205
	v_cvt_pk_bf16_f32 v150, v122, v123
	buffer_store_dwordx4 v[148:151], v147, s[60:63], 0 offen sc1
	v_xor_b32_e32 v126, 16, v205
	v_add_u32_e32 v127, 64, v127
	v_xor_b32_e32 v147, 32, v205
	v_cmp_lt_i32_e64 s[0:1], v126, v127
	s_nop 1
	v_cndmask_b32_e64 v126, v205, v126, s[0:1]
	v_cmp_lt_i32_e64 s[0:1], v147, v127
	v_lshlrev_b32_e32 v126, 2, v126
	s_nop 0
	v_cndmask_b32_e64 v127, v205, v147, s[0:1]
	v_mul_f32_e32 v147, v143, v143
	v_fmac_f32_e32 v147, v142, v142
	v_fmac_f32_e32 v147, v128, v128
	v_fmac_f32_e32 v147, v129, v129
	v_fmac_f32_e32 v147, v122, v122
	v_fmac_f32_e32 v147, v123, v123
	v_fmac_f32_e32 v147, v124, v124
	v_fmac_f32_e32 v147, v125, v125
	s_waitcnt vmcnt(15)
	v_mov_b32_e32 v148, v162
	v_mov_b32_e32 v149, v163
	v_mov_b32_e32 v150, v164
	v_mov_b32_e32 v151, v165
	v_lshlrev_b32_e32 v122, 16, v148
	v_and_b32_e32 v123, 0xffff0000, v148
	v_lshlrev_b32_e32 v124, 16, v149
	v_and_b32_e32 v125, 0xffff0000, v149
	v_pk_add_f32 v[118:119], v[118:119], v[122:123]
	v_pk_add_f32 v[124:125], v[120:121], v[124:125]
	v_mul_f32_e32 v120, v119, v119
	v_fmac_f32_e32 v120, v118, v118
	v_lshlrev_b32_e32 v128, 16, v150
	v_and_b32_e32 v129, 0xffff0000, v150
	v_fmac_f32_e32 v120, v124, v124
	v_pk_add_f32 v[114:115], v[114:115], v[128:129]
	v_fmac_f32_e32 v120, v125, v125
	v_lshlrev_b32_e32 v142, 16, v151
	v_and_b32_e32 v143, 0xffff0000, v151
	v_fmac_f32_e32 v120, v114, v114
	v_pk_add_f32 v[116:117], v[116:117], v[142:143]
	v_fmac_f32_e32 v120, v115, v115
	v_fmac_f32_e32 v120, v116, v116
	v_fmac_f32_e32 v120, v117, v117
	v_add_f32_e32 v128, v147, v120
	ds_bpermute_b32 v129, v126, v128
	v_cvt_pk_bf16_f32 v120, v118, v119
	v_cvt_pk_bf16_f32 v123, v116, v117
	v_lshlrev_b32_e32 v117, 2, v127
	v_or_b32_e32 v116, 0x100, v0
	s_waitcnt lgkmcnt(0)
	v_add_f32_e32 v118, v128, v129
	ds_bpermute_b32 v119, v117, v118
	v_cvt_pk_bf16_f32 v122, v114, v115
	v_or_b32_e32 v114, v116, v146
	v_cvt_pk_bf16_f32 v121, v124, v125
	buffer_store_dwordx4 v[120:123], v114, s[60:63], 0 offen sc1
	v_lshl_add_u64 v[114:115], v[130:131], 3, s[16:17]
	s_and_saveexec_b64 s[0:1], vcc
	s_cbranch_execz .LBB0_646
	s_waitcnt lgkmcnt(0)
	v_add_f32_e32 v118, v118, v119
	v_mul_f32_e32 v118, 0x49800000, v118
	v_trunc_f32_e32 v118, v118
	v_mul_f32_e32 v119, 0x2f800000, v118
	v_floor_f32_e32 v119, v119
	v_fmac_f32_e32 v118, 0xcf800000, v119
	v_cvt_u32_f32_e32 v118, v118
	v_cvt_u32_f32_e32 v119, v119
	global_atomic_add_x2 v[114:115], v[118:119], off
.LBB0_646:
	s_or_b64 exec, exec, s[0:1]
	v_or_b32_e32 v118, 16, v130
	s_waitcnt lgkmcnt(0)
	v_ashrrev_i32_e32 v119, 31, v118
	v_lshlrev_b64 v[118:119], 12, v[118:119]
	v_lshl_add_u64 v[122:123], v[132:133], 0, v[118:119]
	v_add_u32_e32 v127, 0x10800000, v118
	s_waitcnt vmcnt(15)
	v_mov_b32_e32 v118, v166
	v_mov_b32_e32 v119, v167
	v_mov_b32_e32 v120, v168
	v_mov_b32_e32 v121, v169
	v_lshlrev_b32_e32 v124, 16, v118
	v_and_b32_e32 v125, 0xffff0000, v118
	v_lshlrev_b32_e32 v118, 16, v119
	v_and_b32_e32 v119, 0xffff0000, v119
	v_lshlrev_b32_e32 v128, 16, v120
	v_and_b32_e32 v129, 0xffff0000, v120
	v_lshlrev_b32_e32 v120, 16, v121
	v_and_b32_e32 v121, 0xffff0000, v121
	v_pk_add_f32 v[110:111], v[110:111], v[124:125]
	v_pk_add_f32 v[112:113], v[112:113], v[118:119]
	v_pk_add_f32 v[118:119], v[108:109], v[120:121]
	v_mul_f32_e32 v120, v111, v111
	v_fmac_f32_e32 v120, v110, v110
	v_fmac_f32_e32 v120, v112, v112
	v_pk_add_f32 v[108:109], v[106:107], v[128:129]
	v_fmac_f32_e32 v120, v113, v113
	v_fmac_f32_e32 v120, v108, v108
	v_cvt_pk_bf16_f32 v106, v110, v111
	v_or_b32_e32 v110, v127, v0
	v_fmac_f32_e32 v120, v109, v109
	v_cvt_pk_bf16_f32 v107, v112, v113
	v_cvt_pk_bf16_f32 v108, v108, v109
	v_cvt_pk_bf16_f32 v109, v118, v119
	buffer_store_dwordx4 v[106:109], v110, s[60:63], 0 offen sc1
	v_fmac_f32_e32 v120, v118, v118
	v_fmac_f32_e32 v120, v119, v119
	s_waitcnt vmcnt(15)
	v_mov_b32_e32 v106, v170
	v_mov_b32_e32 v107, v171
	v_mov_b32_e32 v108, v172
	v_mov_b32_e32 v109, v173
	v_lshlrev_b32_e32 v110, 16, v106
	v_and_b32_e32 v111, 0xffff0000, v106
	v_lshlrev_b32_e32 v106, 16, v107
	v_and_b32_e32 v107, 0xffff0000, v107
	v_lshlrev_b32_e32 v112, 16, v108
	v_and_b32_e32 v113, 0xffff0000, v108
	v_lshlrev_b32_e32 v108, 16, v109
	v_and_b32_e32 v109, 0xffff0000, v109
	v_pk_add_f32 v[102:103], v[102:103], v[110:111]
	v_pk_add_f32 v[104:105], v[104:105], v[106:107]
	v_pk_add_f32 v[106:107], v[100:101], v[108:109]
	v_pk_add_f32 v[100:101], v[98:99], v[112:113]
	v_mul_f32_e32 v98, v103, v103
	v_fmac_f32_e32 v98, v102, v102
	v_fmac_f32_e32 v98, v104, v104
	v_fmac_f32_e32 v98, v105, v105
	v_fmac_f32_e32 v98, v100, v100
	v_fmac_f32_e32 v98, v101, v101
	v_fmac_f32_e32 v98, v106, v106
	v_fmac_f32_e32 v98, v107, v107
	v_add_f32_e32 v108, v120, v98
	v_cvt_pk_bf16_f32 v98, v102, v103
	v_add_u32_e32 v102, v127, v116
	v_cvt_pk_bf16_f32 v99, v104, v105
	v_cvt_pk_bf16_f32 v100, v100, v101
	v_cvt_pk_bf16_f32 v101, v106, v107
	buffer_store_dwordx4 v[98:101], v102, s[60:63], 0 offen sc1
	ds_bpermute_b32 v98, v126, v108
	s_waitcnt lgkmcnt(0)
	v_add_f32_e32 v98, v108, v98
	ds_bpermute_b32 v99, v117, v98
	s_and_saveexec_b64 s[0:1], vcc
	s_movk_i32 s33, 0x100
	s_cbranch_execz .LBB0_648
	s_waitcnt lgkmcnt(0)
	v_add_f32_e32 v98, v98, v99
	v_mul_f32_e32 v98, 0x49800000, v98
	v_trunc_f32_e32 v98, v98
	v_mul_f32_e32 v99, 0x2f800000, v98
	v_floor_f32_e32 v99, v99
	v_fmac_f32_e32 v98, 0xcf800000, v99
	v_cvt_u32_f32_e32 v98, v98
	v_cvt_u32_f32_e32 v99, v99
	global_atomic_add_x2 v[114:115], v[98:99], off offset:128
; __device__ __forceinline__ unsigned cvt_pk_bf16(float lo, float hi) { unsigned r; asm("v_cvt_pk_bf16_f32 %0, %1, %2" : "=v"(r) : "v"(lo), "v"(hi)); return r; }
; __device__ __forceinline__ float bflo(unsigned w) { return __uint_as_float(w << 16); }
; __device__ __forceinline__ float bfhi(unsigned w) { return __uint_as_float(w & 0xffff0000u); }
; #define WT_STORE16(ptr, val) __builtin_amdgcn_raw_buffer_store_b128((val), wsr, (int)((const char*)(ptr) - (const char*)ws), 0, 16)
; template <int MODE>
; __device__ __forceinline__ void gemm_epilogue(const Params& p, int l, const f32x4 (&acc)[2][2][4][2], const Unit& u, int wr, int wc, int fr, int fq, const LAS float* rl, int pm0) {
;     ...
; #pragma unroll
;         for (int ai = 0; ai < 2; ++ai)
; #pragma unroll
;             for (int m = 0; m < 4; ++m) {
;                 const int tok = u.pm * 256 + 128 * ai + 64 * wr + 16 * m + fr;
;                 float part = 0.f;
; #pragma unroll
;                 for (int bj = 0; bj < 2; ++bj) {
;                     const size_t idx = (size_t)tok * 2048 + u.pn * 256 + 128 * bj + 32 * wc + 8 * fq;
;                     const u32x4 xw = *(const u32x4*)(xb + idx);
;                     f32x4 y0 = (f32x4){bflo(xw.x), bfhi(xw.x), bflo(xw.y), bfhi(xw.y)}, y1 = (f32x4){bflo(xw.z), bfhi(xw.z), bflo(xw.w), bfhi(xw.w)};
;                     y0 += acc[ai][bj][m][0]; y1 += acc[ai][bj][m][1];
;                     part += y0[0] * y0[0] + y0[1] * y0[1] + y0[2] * y0[2] + y0[3] * y0[3] + y1[0] * y1[0] + y1[1] * y1[1] + y1[2] * y1[2] + y1[3] * y1[3];
;                     u32x4 w; w.x = cvt_pk_bf16(y0[0], y0[1]); w.y = cvt_pk_bf16(y0[2], y0[3]); w.z = cvt_pk_bf16(y1[0], y1[1]); w.w = cvt_pk_bf16(y1[2], y1[3]);
;                     WT_STORE16(xb + idx, w);
;                 }
;                 part += __shfl_xor(part, 16); part += __shfl_xor(part, 32);
;                 if (fq == 0) atomicAdd(ssn + tok, (u64)(part * SS_SCALE));
;             }
.LBB0_648:
	s_or_b64 exec, exec, s[0:1]
	v_or_b32_e32 v98, 32, v130
	s_waitcnt lgkmcnt(0)
	v_ashrrev_i32_e32 v99, 31, v98
	v_lshlrev_b64 v[98:99], 12, v[98:99]
	v_lshl_add_u64 v[102:103], v[132:133], 0, v[98:99]
	v_add_u32_e32 v108, 0x10800000, v98
	s_waitcnt vmcnt(15)
	v_mov_b32_e32 v98, v174
	v_mov_b32_e32 v99, v175
	v_mov_b32_e32 v100, v176
	v_mov_b32_e32 v101, v177
	v_lshlrev_b32_e32 v104, 16, v98
	v_and_b32_e32 v105, 0xffff0000, v98
	v_lshlrev_b32_e32 v98, 16, v99
	v_and_b32_e32 v99, 0xffff0000, v99
	v_lshlrev_b32_e32 v106, 16, v100
	v_and_b32_e32 v107, 0xffff0000, v100
	v_lshlrev_b32_e32 v100, 16, v101
	v_and_b32_e32 v101, 0xffff0000, v101
	v_pk_add_f32 v[94:95], v[94:95], v[104:105]
	v_pk_add_f32 v[96:97], v[96:97], v[98:99]
	v_pk_add_f32 v[98:99], v[92:93], v[100:101]
	v_mul_f32_e32 v100, v95, v95
	v_fmac_f32_e32 v100, v94, v94
	v_fmac_f32_e32 v100, v96, v96
	v_pk_add_f32 v[92:93], v[90:91], v[106:107]
	v_fmac_f32_e32 v100, v97, v97
	v_fmac_f32_e32 v100, v92, v92
	v_cvt_pk_bf16_f32 v90, v94, v95
	v_or_b32_e32 v94, v108, v0
	v_fmac_f32_e32 v100, v93, v93
	v_cvt_pk_bf16_f32 v91, v96, v97
	v_cvt_pk_bf16_f32 v92, v92, v93
	v_cvt_pk_bf16_f32 v93, v98, v99
	buffer_store_dwordx4 v[90:93], v94, s[60:63], 0 offen sc1
	v_fmac_f32_e32 v100, v98, v98
	v_fmac_f32_e32 v100, v99, v99
	s_waitcnt vmcnt(15)
	v_mov_b32_e32 v90, v178
	v_mov_b32_e32 v91, v179
	v_mov_b32_e32 v92, v180
	v_mov_b32_e32 v93, v181
	v_lshlrev_b32_e32 v94, 16, v90
	v_and_b32_e32 v95, 0xffff0000, v90
	v_lshlrev_b32_e32 v90, 16, v91
	v_and_b32_e32 v91, 0xffff0000, v91
	v_lshlrev_b32_e32 v96, 16, v92
	v_and_b32_e32 v97, 0xffff0000, v92
	v_lshlrev_b32_e32 v92, 16, v93
	v_and_b32_e32 v93, 0xffff0000, v93
	v_pk_add_f32 v[86:87], v[86:87], v[94:95]
	v_pk_add_f32 v[88:89], v[88:89], v[90:91]
	v_pk_add_f32 v[90:91], v[84:85], v[92:93]
	v_pk_add_f32 v[84:85], v[82:83], v[96:97]
	v_mul_f32_e32 v82, v87, v87
	v_fmac_f32_e32 v82, v86, v86
	v_fmac_f32_e32 v82, v88, v88
	v_fmac_f32_e32 v82, v89, v89
	v_fmac_f32_e32 v82, v84, v84
	v_fmac_f32_e32 v82, v85, v85
	v_fmac_f32_e32 v82, v90, v90
	v_fmac_f32_e32 v82, v91, v91
	v_add_f32_e32 v92, v100, v82
	v_cvt_pk_bf16_f32 v82, v86, v87
	v_add_u32_e32 v86, v108, v116
	v_cvt_pk_bf16_f32 v83, v88, v89
	v_cvt_pk_bf16_f32 v84, v84, v85
	v_cvt_pk_bf16_f32 v85, v90, v91
	buffer_store_dwordx4 v[82:85], v86, s[60:63], 0 offen sc1
	ds_bpermute_b32 v82, v126, v92
	s_waitcnt lgkmcnt(0)
	v_add_f32_e32 v82, v92, v82
	ds_bpermute_b32 v83, v117, v82
	s_and_saveexec_b64 s[0:1], vcc
	s_cbranch_execz .LBB0_650
	s_waitcnt lgkmcnt(0)
	v_add_f32_e32 v82, v82, v83
	v_mul_f32_e32 v82, 0x49800000, v82
	v_trunc_f32_e32 v82, v82
	v_mul_f32_e32 v83, 0x2f800000, v82
	v_floor_f32_e32 v83, v83
	v_fmac_f32_e32 v82, 0xcf800000, v83
	v_cvt_u32_f32_e32 v82, v82
	v_cvt_u32_f32_e32 v83, v83
	global_atomic_add_x2 v[114:115], v[82:83], off offset:256
.LBB0_650:
	s_or_b64 exec, exec, s[0:1]
	v_or_b32_e32 v82, 48, v130
	s_waitcnt lgkmcnt(0)
	v_ashrrev_i32_e32 v83, 31, v82
	v_lshlrev_b64 v[82:83], 12, v[82:83]
	v_lshl_add_u64 v[86:87], v[132:133], 0, v[82:83]
	v_add_u32_e32 v92, 0x10800000, v82
	s_waitcnt vmcnt(15)
	v_mov_b32_e32 v82, v182
	v_mov_b32_e32 v83, v183
	v_mov_b32_e32 v84, v184
	v_mov_b32_e32 v85, v185
	v_lshlrev_b32_e32 v88, 16, v82
	v_and_b32_e32 v89, 0xffff0000, v82
	v_lshlrev_b32_e32 v82, 16, v83
	v_and_b32_e32 v83, 0xffff0000, v83
	v_lshlrev_b32_e32 v90, 16, v84
	v_and_b32_e32 v91, 0xffff0000, v84
	v_lshlrev_b32_e32 v84, 16, v85
	v_and_b32_e32 v85, 0xffff0000, v85
	v_pk_add_f32 v[78:79], v[78:79], v[88:89]
	v_pk_add_f32 v[80:81], v[80:81], v[82:83]
	v_pk_add_f32 v[82:83], v[76:77], v[84:85]
	v_mul_f32_e32 v84, v79, v79
	v_fmac_f32_e32 v84, v78, v78
	v_fmac_f32_e32 v84, v80, v80
	v_pk_add_f32 v[76:77], v[74:75], v[90:91]
	v_fmac_f32_e32 v84, v81, v81
	v_fmac_f32_e32 v84, v76, v76
	v_cvt_pk_bf16_f32 v74, v78, v79
	v_or_b32_e32 v78, v92, v0
	v_fmac_f32_e32 v84, v77, v77
	v_cvt_pk_bf16_f32 v75, v80, v81
	v_cvt_pk_bf16_f32 v76, v76, v77
	v_cvt_pk_bf16_f32 v77, v82, v83
	buffer_store_dwordx4 v[74:77], v78, s[60:63], 0 offen sc1
	v_fmac_f32_e32 v84, v82, v82
	v_fmac_f32_e32 v84, v83, v83
	s_waitcnt vmcnt(15)
	v_mov_b32_e32 v74, v186
	v_mov_b32_e32 v75, v187
	v_mov_b32_e32 v76, v188
	v_mov_b32_e32 v77, v189
	v_lshlrev_b32_e32 v78, 16, v74
	v_and_b32_e32 v79, 0xffff0000, v74
	v_lshlrev_b32_e32 v74, 16, v75
	v_and_b32_e32 v75, 0xffff0000, v75
	v_lshlrev_b32_e32 v80, 16, v76
	v_and_b32_e32 v81, 0xffff0000, v76
	v_lshlrev_b32_e32 v76, 16, v77
	v_and_b32_e32 v77, 0xffff0000, v77
	v_pk_add_f32 v[70:71], v[70:71], v[78:79]
	v_pk_add_f32 v[72:73], v[72:73], v[74:75]
	v_pk_add_f32 v[74:75], v[68:69], v[76:77]
	v_pk_add_f32 v[68:69], v[66:67], v[80:81]
	v_mul_f32_e32 v66, v71, v71
	v_fmac_f32_e32 v66, v70, v70
	v_fmac_f32_e32 v66, v72, v72
	v_fmac_f32_e32 v66, v73, v73
	v_fmac_f32_e32 v66, v68, v68
	v_fmac_f32_e32 v66, v69, v69
	v_fmac_f32_e32 v66, v74, v74
	v_fmac_f32_e32 v66, v75, v75
	v_add_f32_e32 v76, v84, v66
	v_cvt_pk_bf16_f32 v66, v70, v71
	v_add_u32_e32 v70, v92, v116
	v_cvt_pk_bf16_f32 v67, v72, v73
	v_cvt_pk_bf16_f32 v68, v68, v69
	v_cvt_pk_bf16_f32 v69, v74, v75
	buffer_store_dwordx4 v[66:69], v70, s[60:63], 0 offen sc1
	ds_bpermute_b32 v66, v126, v76
	s_waitcnt lgkmcnt(0)
	v_add_f32_e32 v66, v76, v66
	ds_bpermute_b32 v67, v117, v66
	s_and_saveexec_b64 s[0:1], vcc
	v_readlane_b32 s84, v252, 43
	s_mov_b32 s96, 0x8400
	s_cbranch_execz .LBB0_652
	s_waitcnt lgkmcnt(0)
	v_add_f32_e32 v66, v66, v67
	v_mul_f32_e32 v66, 0x49800000, v66
	v_trunc_f32_e32 v66, v66
	v_mul_f32_e32 v67, 0x2f800000, v66
	v_floor_f32_e32 v67, v67
	v_fmac_f32_e32 v66, 0xcf800000, v67
	v_cvt_u32_f32_e32 v66, v66
	v_cvt_u32_f32_e32 v67, v67
	global_atomic_add_x2 v[114:115], v[66:67], off offset:384
; __device__ __forceinline__ unsigned cvt_pk_bf16(float lo, float hi) { unsigned r; asm("v_cvt_pk_bf16_f32 %0, %1, %2" : "=v"(r) : "v"(lo), "v"(hi)); return r; }
; __device__ __forceinline__ float bflo(unsigned w) { return __uint_as_float(w << 16); }
; __device__ __forceinline__ float bfhi(unsigned w) { return __uint_as_float(w & 0xffff0000u); }
; #define WT_STORE16(ptr, val) __builtin_amdgcn_raw_buffer_store_b128((val), wsr, (int)((const char*)(ptr) - (const char*)ws), 0, 16)
; template <int MODE>
; __device__ __forceinline__ void gemm_epilogue(const Params& p, int l, const f32x4 (&acc)[2][2][4][2], const Unit& u, int wr, int wc, int fr, int fq, const LAS float* rl, int pm0) {
;     ...
; #pragma unroll
;         for (int ai = 0; ai < 2; ++ai)
; #pragma unroll
;             for (int m = 0; m < 4; ++m) {
;                 const int tok = u.pm * 256 + 128 * ai + 64 * wr + 16 * m + fr;
;                 float part = 0.f;
; #pragma unroll
;                 for (int bj = 0; bj < 2; ++bj) {
;                     const size_t idx = (size_t)tok * 2048 + u.pn * 256 + 128 * bj + 32 * wc + 8 * fq;
;                     const u32x4 xw = *(const u32x4*)(xb + idx);
;                     f32x4 y0 = (f32x4){bflo(xw.x), bfhi(xw.x), bflo(xw.y), bfhi(xw.y)}, y1 = (f32x4){bflo(xw.z), bfhi(xw.z), bflo(xw.w), bfhi(xw.w)};
;                     y0 += acc[ai][bj][m][0]; y1 += acc[ai][bj][m][1];
;                     part += y0[0] * y0[0] + y0[1] * y0[1] + y0[2] * y0[2] + y0[3] * y0[3] + y1[0] * y1[0] + y1[1] * y1[1] + y1[2] * y1[2] + y1[3] * y1[3];
;                     u32x4 w; w.x = cvt_pk_bf16(y0[0], y0[1]); w.y = cvt_pk_bf16(y0[2], y0[3]); w.z = cvt_pk_bf16(y1[0], y1[1]); w.w = cvt_pk_bf16(y1[2], y1[3]);
;                     WT_STORE16(xb + idx, w);
;                 }
;                 part += __shfl_xor(part, 16); part += __shfl_xor(part, 32);
;                 if (fq == 0) atomicAdd(ssn + tok, (u64)(part * SS_SCALE));
;             }
.LBB0_652:
	s_or_b64 exec, exec, s[0:1]
	v_add_u32_e32 v66, 0x80, v130
	s_waitcnt lgkmcnt(0)
	v_ashrrev_i32_e32 v67, 31, v66
	v_lshlrev_b64 v[66:67], 12, v[66:67]
	v_lshl_add_u64 v[70:71], v[132:133], 0, v[66:67]
	v_add_u32_e32 v76, 0x10800000, v66
	s_waitcnt vmcnt(15)
	v_mov_b32_e32 v66, v190
	v_mov_b32_e32 v67, v191
	v_mov_b32_e32 v68, v192
	v_mov_b32_e32 v69, v193
	v_lshlrev_b32_e32 v72, 16, v66
	v_and_b32_e32 v73, 0xffff0000, v66
	v_lshlrev_b32_e32 v66, 16, v67
	v_and_b32_e32 v67, 0xffff0000, v67
	v_lshlrev_b32_e32 v74, 16, v68
	v_and_b32_e32 v75, 0xffff0000, v68
	v_lshlrev_b32_e32 v68, 16, v69
	v_and_b32_e32 v69, 0xffff0000, v69
	v_pk_add_f32 v[62:63], v[62:63], v[72:73]
	v_pk_add_f32 v[64:65], v[64:65], v[66:67]
	v_pk_add_f32 v[66:67], v[60:61], v[68:69]
	v_mul_f32_e32 v68, v63, v63
	v_fmac_f32_e32 v68, v62, v62
	v_fmac_f32_e32 v68, v64, v64
	v_pk_add_f32 v[60:61], v[58:59], v[74:75]
	v_fmac_f32_e32 v68, v65, v65
	v_fmac_f32_e32 v68, v60, v60
	v_cvt_pk_bf16_f32 v58, v62, v63
	v_or_b32_e32 v62, v76, v0
	v_fmac_f32_e32 v68, v61, v61
	v_cvt_pk_bf16_f32 v59, v64, v65
	v_cvt_pk_bf16_f32 v60, v60, v61
	v_cvt_pk_bf16_f32 v61, v66, v67
	buffer_store_dwordx4 v[58:61], v62, s[60:63], 0 offen sc1
	v_fmac_f32_e32 v68, v66, v66
	v_fmac_f32_e32 v68, v67, v67
	s_waitcnt vmcnt(15)
	v_mov_b32_e32 v58, v194
	v_mov_b32_e32 v59, v195
	v_mov_b32_e32 v60, v196
	v_mov_b32_e32 v61, v197
	v_lshlrev_b32_e32 v62, 16, v58
	v_and_b32_e32 v63, 0xffff0000, v58
	v_lshlrev_b32_e32 v58, 16, v59
	v_and_b32_e32 v59, 0xffff0000, v59
	v_lshlrev_b32_e32 v64, 16, v60
	v_and_b32_e32 v65, 0xffff0000, v60
	v_lshlrev_b32_e32 v60, 16, v61
	v_and_b32_e32 v61, 0xffff0000, v61
	v_pk_add_f32 v[54:55], v[54:55], v[62:63]
	v_pk_add_f32 v[56:57], v[56:57], v[58:59]
	v_pk_add_f32 v[58:59], v[52:53], v[60:61]
	v_pk_add_f32 v[52:53], v[50:51], v[64:65]
	v_mul_f32_e32 v50, v55, v55
	v_fmac_f32_e32 v50, v54, v54
	v_fmac_f32_e32 v50, v56, v56
	v_fmac_f32_e32 v50, v57, v57
	v_fmac_f32_e32 v50, v52, v52
	v_fmac_f32_e32 v50, v53, v53
	v_fmac_f32_e32 v50, v58, v58
	v_fmac_f32_e32 v50, v59, v59
	v_add_f32_e32 v60, v68, v50
	v_cvt_pk_bf16_f32 v50, v54, v55
	v_add_u32_e32 v54, v76, v116
	v_cvt_pk_bf16_f32 v51, v56, v57
	v_cvt_pk_bf16_f32 v52, v52, v53
	v_cvt_pk_bf16_f32 v53, v58, v59
	buffer_store_dwordx4 v[50:53], v54, s[60:63], 0 offen sc1
	ds_bpermute_b32 v50, v126, v60
	s_waitcnt lgkmcnt(0)
	v_add_f32_e32 v50, v60, v50
	ds_bpermute_b32 v51, v117, v50
	s_and_saveexec_b64 s[0:1], vcc
	s_cbranch_execz .LBB0_654
	s_waitcnt lgkmcnt(0)
	v_add_f32_e32 v50, v50, v51
	v_mul_f32_e32 v50, 0x49800000, v50
	v_trunc_f32_e32 v50, v50
	v_mul_f32_e32 v51, 0x2f800000, v50
	v_floor_f32_e32 v51, v51
	v_fmac_f32_e32 v50, 0xcf800000, v51
	v_cvt_u32_f32_e32 v50, v50
	v_cvt_u32_f32_e32 v51, v51
	global_atomic_add_x2 v[114:115], v[50:51], off offset:1024
.LBB0_654:
	s_or_b64 exec, exec, s[0:1]
	v_add_u32_e32 v50, 0x90, v130
	s_waitcnt lgkmcnt(0)
	v_ashrrev_i32_e32 v51, 31, v50
	v_lshlrev_b64 v[50:51], 12, v[50:51]
	v_lshl_add_u64 v[54:55], v[132:133], 0, v[50:51]
	v_add_u32_e32 v60, 0x10800000, v50
	s_waitcnt vmcnt(15)
	v_mov_b32_e32 v50, v208
	v_mov_b32_e32 v51, v209
	v_mov_b32_e32 v52, v210
	v_mov_b32_e32 v53, v211
	v_lshlrev_b32_e32 v56, 16, v50
	v_and_b32_e32 v57, 0xffff0000, v50
	v_lshlrev_b32_e32 v50, 16, v51
	v_and_b32_e32 v51, 0xffff0000, v51
	v_lshlrev_b32_e32 v58, 16, v52
	v_and_b32_e32 v59, 0xffff0000, v52
	v_lshlrev_b32_e32 v52, 16, v53
	v_and_b32_e32 v53, 0xffff0000, v53
	v_pk_add_f32 v[46:47], v[46:47], v[56:57]
	v_pk_add_f32 v[48:49], v[48:49], v[50:51]
	v_pk_add_f32 v[50:51], v[44:45], v[52:53]
	v_mul_f32_e32 v52, v47, v47
	v_fmac_f32_e32 v52, v46, v46
	v_fmac_f32_e32 v52, v48, v48
	v_pk_add_f32 v[44:45], v[42:43], v[58:59]
	v_fmac_f32_e32 v52, v49, v49
	v_fmac_f32_e32 v52, v44, v44
	v_cvt_pk_bf16_f32 v42, v46, v47
	v_or_b32_e32 v46, v60, v0
	v_fmac_f32_e32 v52, v45, v45
	v_cvt_pk_bf16_f32 v43, v48, v49
	v_cvt_pk_bf16_f32 v44, v44, v45
	v_cvt_pk_bf16_f32 v45, v50, v51
	buffer_store_dwordx4 v[42:45], v46, s[60:63], 0 offen sc1
	v_fmac_f32_e32 v52, v50, v50
	v_fmac_f32_e32 v52, v51, v51
	s_waitcnt vmcnt(15)
	v_mov_b32_e32 v42, v212
	v_mov_b32_e32 v43, v213
	v_mov_b32_e32 v44, v214
	v_mov_b32_e32 v45, v215
	v_lshlrev_b32_e32 v46, 16, v42
	v_and_b32_e32 v47, 0xffff0000, v42
	v_lshlrev_b32_e32 v42, 16, v43
	v_and_b32_e32 v43, 0xffff0000, v43
	v_lshlrev_b32_e32 v48, 16, v44
	v_and_b32_e32 v49, 0xffff0000, v44
	v_lshlrev_b32_e32 v44, 16, v45
	v_and_b32_e32 v45, 0xffff0000, v45
	v_pk_add_f32 v[38:39], v[38:39], v[46:47]
	v_pk_add_f32 v[40:41], v[40:41], v[42:43]
	v_pk_add_f32 v[42:43], v[36:37], v[44:45]
	v_pk_add_f32 v[36:37], v[34:35], v[48:49]
	v_mul_f32_e32 v34, v39, v39
	v_fmac_f32_e32 v34, v38, v38
	v_fmac_f32_e32 v34, v40, v40
	v_fmac_f32_e32 v34, v41, v41
	v_fmac_f32_e32 v34, v36, v36
	v_fmac_f32_e32 v34, v37, v37
	v_fmac_f32_e32 v34, v42, v42
	v_fmac_f32_e32 v34, v43, v43
	v_add_f32_e32 v44, v52, v34
	v_cvt_pk_bf16_f32 v34, v38, v39
	v_add_u32_e32 v38, v60, v116
	v_cvt_pk_bf16_f32 v35, v40, v41
	v_cvt_pk_bf16_f32 v36, v36, v37
	v_cvt_pk_bf16_f32 v37, v42, v43
	buffer_store_dwordx4 v[34:37], v38, s[60:63], 0 offen sc1
	ds_bpermute_b32 v34, v126, v44
	s_waitcnt lgkmcnt(0)
	v_add_f32_e32 v34, v44, v34
	ds_bpermute_b32 v35, v117, v34
	s_and_saveexec_b64 s[0:1], vcc
	s_cbranch_execz .LBB0_656
	s_waitcnt lgkmcnt(0)
	v_add_f32_e32 v34, v34, v35
	v_mul_f32_e32 v34, 0x49800000, v34
	v_trunc_f32_e32 v34, v34
	v_mul_f32_e32 v35, 0x2f800000, v34
	v_floor_f32_e32 v35, v35
	v_fmac_f32_e32 v34, 0xcf800000, v35
	v_cvt_u32_f32_e32 v34, v34
	v_cvt_u32_f32_e32 v35, v35
	global_atomic_add_x2 v[114:115], v[34:35], off offset:1152
; __device__ __forceinline__ unsigned cvt_pk_bf16(float lo, float hi) { unsigned r; asm("v_cvt_pk_bf16_f32 %0, %1, %2" : "=v"(r) : "v"(lo), "v"(hi)); return r; }
; __device__ __forceinline__ float bflo(unsigned w) { return __uint_as_float(w << 16); }
; __device__ __forceinline__ float bfhi(unsigned w) { return __uint_as_float(w & 0xffff0000u); }
; #define WT_STORE16(ptr, val) __builtin_amdgcn_raw_buffer_store_b128((val), wsr, (int)((const char*)(ptr) - (const char*)ws), 0, 16)
; template <int MODE>
; __device__ __forceinline__ void gemm_epilogue(const Params& p, int l, const f32x4 (&acc)[2][2][4][2], const Unit& u, int wr, int wc, int fr, int fq, const LAS float* rl, int pm0) {
;     ...
; #pragma unroll
;         for (int ai = 0; ai < 2; ++ai)
; #pragma unroll
;             for (int m = 0; m < 4; ++m) {
;                 const int tok = u.pm * 256 + 128 * ai + 64 * wr + 16 * m + fr;
;                 float part = 0.f;
; #pragma unroll
;                 for (int bj = 0; bj < 2; ++bj) {
;                     const size_t idx = (size_t)tok * 2048 + u.pn * 256 + 128 * bj + 32 * wc + 8 * fq;
;                     const u32x4 xw = *(const u32x4*)(xb + idx);
;                     f32x4 y0 = (f32x4){bflo(xw.x), bfhi(xw.x), bflo(xw.y), bfhi(xw.y)}, y1 = (f32x4){bflo(xw.z), bfhi(xw.z), bflo(xw.w), bfhi(xw.w)};
;                     y0 += acc[ai][bj][m][0]; y1 += acc[ai][bj][m][1];
;                     part += y0[0] * y0[0] + y0[1] * y0[1] + y0[2] * y0[2] + y0[3] * y0[3] + y1[0] * y1[0] + y1[1] * y1[1] + y1[2] * y1[2] + y1[3] * y1[3];
;                     u32x4 w; w.x = cvt_pk_bf16(y0[0], y0[1]); w.y = cvt_pk_bf16(y0[2], y0[3]); w.z = cvt_pk_bf16(y1[0], y1[1]); w.w = cvt_pk_bf16(y1[2], y1[3]);
;                     WT_STORE16(xb + idx, w);
;                 }
;                 part += __shfl_xor(part, 16); part += __shfl_xor(part, 32);
;                 if (fq == 0) atomicAdd(ssn + tok, (u64)(part * SS_SCALE));
;             }
.LBB0_656:
	s_or_b64 exec, exec, s[0:1]
	v_add_u32_e32 v34, 0xa0, v130
	s_waitcnt lgkmcnt(0)
	v_ashrrev_i32_e32 v35, 31, v34
	v_lshlrev_b64 v[34:35], 12, v[34:35]
	v_lshl_add_u64 v[38:39], v[132:133], 0, v[34:35]
	v_add_u32_e32 v44, 0x10800000, v34
	s_waitcnt vmcnt(15)
	v_mov_b32_e32 v34, v216
	v_mov_b32_e32 v35, v217
	v_mov_b32_e32 v36, v218
	v_mov_b32_e32 v37, v219
	v_lshlrev_b32_e32 v40, 16, v34
	v_and_b32_e32 v41, 0xffff0000, v34
	v_lshlrev_b32_e32 v34, 16, v35
	v_and_b32_e32 v35, 0xffff0000, v35
	v_lshlrev_b32_e32 v42, 16, v36
	v_and_b32_e32 v43, 0xffff0000, v36
	v_lshlrev_b32_e32 v36, 16, v37
	v_and_b32_e32 v37, 0xffff0000, v37
	v_pk_add_f32 v[30:31], v[30:31], v[40:41]
	v_pk_add_f32 v[32:33], v[32:33], v[34:35]
	v_pk_add_f32 v[34:35], v[28:29], v[36:37]
	v_mul_f32_e32 v36, v31, v31
	v_fmac_f32_e32 v36, v30, v30
	v_fmac_f32_e32 v36, v32, v32
	v_pk_add_f32 v[28:29], v[26:27], v[42:43]
	v_fmac_f32_e32 v36, v33, v33
	v_fmac_f32_e32 v36, v28, v28
	v_cvt_pk_bf16_f32 v26, v30, v31
	v_or_b32_e32 v30, v44, v0
	v_fmac_f32_e32 v36, v29, v29
	v_cvt_pk_bf16_f32 v27, v32, v33
	v_cvt_pk_bf16_f32 v28, v28, v29
	v_cvt_pk_bf16_f32 v29, v34, v35
	buffer_store_dwordx4 v[26:29], v30, s[60:63], 0 offen sc1
	v_fmac_f32_e32 v36, v34, v34
	v_fmac_f32_e32 v36, v35, v35
	s_waitcnt vmcnt(15)
	v_mov_b32_e32 v26, v220
	v_mov_b32_e32 v27, v221
	v_mov_b32_e32 v28, v222
	v_mov_b32_e32 v29, v223
	v_lshlrev_b32_e32 v30, 16, v26
	v_and_b32_e32 v31, 0xffff0000, v26
	v_lshlrev_b32_e32 v26, 16, v27
	v_and_b32_e32 v27, 0xffff0000, v27
	v_lshlrev_b32_e32 v32, 16, v28
	v_and_b32_e32 v33, 0xffff0000, v28
	v_lshlrev_b32_e32 v28, 16, v29
	v_and_b32_e32 v29, 0xffff0000, v29
	v_pk_add_f32 v[22:23], v[22:23], v[30:31]
	v_pk_add_f32 v[24:25], v[24:25], v[26:27]
	v_pk_add_f32 v[26:27], v[20:21], v[28:29]
	v_pk_add_f32 v[20:21], v[18:19], v[32:33]
	v_mul_f32_e32 v18, v23, v23
	v_fmac_f32_e32 v18, v22, v22
	v_fmac_f32_e32 v18, v24, v24
	v_fmac_f32_e32 v18, v25, v25
	v_fmac_f32_e32 v18, v20, v20
	v_fmac_f32_e32 v18, v21, v21
	v_fmac_f32_e32 v18, v26, v26
	v_fmac_f32_e32 v18, v27, v27
	v_add_f32_e32 v28, v36, v18
	v_cvt_pk_bf16_f32 v18, v22, v23
	v_add_u32_e32 v22, v44, v116
	v_cvt_pk_bf16_f32 v19, v24, v25
	v_cvt_pk_bf16_f32 v20, v20, v21
	v_cvt_pk_bf16_f32 v21, v26, v27
	buffer_store_dwordx4 v[18:21], v22, s[60:63], 0 offen sc1
	ds_bpermute_b32 v18, v126, v28
	s_waitcnt lgkmcnt(0)
	v_add_f32_e32 v18, v28, v18
	ds_bpermute_b32 v19, v117, v18
	s_and_saveexec_b64 s[0:1], vcc
	s_cbranch_execz .LBB0_658
	s_waitcnt lgkmcnt(0)
	v_add_f32_e32 v18, v18, v19
	v_mul_f32_e32 v18, 0x49800000, v18
	v_trunc_f32_e32 v18, v18
	v_mul_f32_e32 v19, 0x2f800000, v18
	v_floor_f32_e32 v19, v19
	v_fmac_f32_e32 v18, 0xcf800000, v19
	v_cvt_u32_f32_e32 v18, v18
	v_cvt_u32_f32_e32 v19, v19
	global_atomic_add_x2 v[114:115], v[18:19], off offset:1280
.LBB0_658:
	s_or_b64 exec, exec, s[0:1]
	v_add_u32_e32 v18, 0xb0, v130
	s_waitcnt lgkmcnt(0)
	v_ashrrev_i32_e32 v19, 31, v18
	v_lshlrev_b64 v[22:23], 12, v[18:19]
	v_lshl_add_u64 v[24:25], v[132:133], 0, v[22:23]
	v_add_u32_e32 v28, 0x10800000, v22
	v_or_b32_e32 v0, v28, v0
	s_waitcnt vmcnt(15)
	v_mov_b32_e32 v18, v224
	v_mov_b32_e32 v19, v225
	v_mov_b32_e32 v20, v226
	v_mov_b32_e32 v21, v227
	v_lshlrev_b32_e32 v22, 16, v18
	v_and_b32_e32 v23, 0xffff0000, v18
	v_lshlrev_b32_e32 v18, 16, v19
	v_and_b32_e32 v19, 0xffff0000, v19
	v_lshlrev_b32_e32 v26, 16, v20
	v_and_b32_e32 v27, 0xffff0000, v20
	v_lshlrev_b32_e32 v20, 16, v21
	v_and_b32_e32 v21, 0xffff0000, v21
	v_pk_add_f32 v[16:17], v[16:17], v[18:19]
	v_pk_add_f32 v[14:15], v[14:15], v[22:23]
	v_pk_add_f32 v[18:19], v[12:13], v[20:21]
	v_pk_add_f32 v[20:21], v[10:11], v[26:27]
	v_cvt_pk_bf16_f32 v10, v14, v15
	v_cvt_pk_bf16_f32 v11, v16, v17
	v_cvt_pk_bf16_f32 v13, v18, v19
	s_nop 0
	v_cvt_pk_bf16_f32 v12, v20, v21
	buffer_store_dwordx4 v[10:13], v0, s[60:63], 0 offen sc1
	v_mul_f32_e32 v0, v15, v15
	v_fmac_f32_e32 v0, v14, v14
	v_fmac_f32_e32 v0, v16, v16
	v_fmac_f32_e32 v0, v17, v17
	v_fmac_f32_e32 v0, v20, v20
	v_fmac_f32_e32 v0, v21, v21
	v_fmac_f32_e32 v0, v18, v18
	v_fmac_f32_e32 v0, v19, v19
	s_waitcnt vmcnt(15)
	v_mov_b32_e32 v10, v228
	v_mov_b32_e32 v11, v229
	v_mov_b32_e32 v12, v230
	v_mov_b32_e32 v13, v231
	v_lshlrev_b32_e32 v14, 16, v10
	v_and_b32_e32 v15, 0xffff0000, v10
	v_lshlrev_b32_e32 v10, 16, v11
	v_and_b32_e32 v11, 0xffff0000, v11
	v_lshlrev_b32_e32 v16, 16, v12
	v_and_b32_e32 v17, 0xffff0000, v12
	v_lshlrev_b32_e32 v12, 16, v13
	v_and_b32_e32 v13, 0xffff0000, v13
	v_pk_add_f32 v[6:7], v[6:7], v[14:15]
	v_pk_add_f32 v[8:9], v[8:9], v[10:11]
	v_pk_add_f32 v[10:11], v[4:5], v[12:13]
	v_pk_add_f32 v[12:13], v[2:3], v[16:17]
	v_mul_f32_e32 v2, v7, v7
	v_fmac_f32_e32 v2, v6, v6
	v_fmac_f32_e32 v2, v8, v8
	v_fmac_f32_e32 v2, v9, v9
	v_fmac_f32_e32 v2, v12, v12
	v_fmac_f32_e32 v2, v13, v13
	v_fmac_f32_e32 v2, v10, v10
	v_fmac_f32_e32 v2, v11, v11
	v_add_f32_e32 v0, v0, v2
	ds_bpermute_b32 v2, v126, v0
	v_add_u32_e32 v3, v28, v116
	v_cvt_pk_bf16_f32 v4, v6, v7
	v_cvt_pk_bf16_f32 v5, v8, v9
	v_cvt_pk_bf16_f32 v6, v12, v13
	s_waitcnt lgkmcnt(0)
	v_add_f32_e32 v0, v0, v2
	ds_bpermute_b32 v2, v117, v0
	v_cvt_pk_bf16_f32 v7, v10, v11
	buffer_store_dwordx4 v[4:7], v3, s[60:63], 0 offen sc1
	s_and_saveexec_b64 s[0:1], vcc
	s_cbranch_execz .LBB0_660
	s_waitcnt lgkmcnt(0)
	v_add_f32_e32 v0, v0, v2
	v_mul_f32_e32 v0, 0x49800000, v0
	v_trunc_f32_e32 v0, v0
	v_mul_f32_e32 v2, 0x2f800000, v0
	v_floor_f32_e32 v3, v2
	v_fmac_f32_e32 v0, 0xcf800000, v3
	v_cvt_u32_f32_e32 v2, v0
	v_cvt_u32_f32_e32 v3, v3
	global_atomic_add_x2 v[114:115], v[2:3], off offset:1408

; #define PG8_STAGE(bufoff, gbase, voff) do { _Pragma("unroll") for (int _i = 0; _i < 2; ++_i) \
;         __builtin_amdgcn_global_load_lds((const unsigned*)((const char*)(gbase) + (voff)[_i]), (LAS unsigned*)(lds + (bufoff) + ldsw + _i * 8192), 16, 0, 0); } while (0)
; #define PG8_LDA(dst, b, h) do { _Pragma("unroll") for (int m = 0; m < 4; ++m) _Pragma("unroll") for (int k = 0; k < 2; ++k) dst[m][k] = *(const LAS bf16x8*)(lds + PG8_SA(b, h) + aoff + m * 2048 + k * 1024); } while (0)
; #define PG8_WAIT_V(n) asm volatile("s_waitcnt vmcnt(" #n ")" ::: "memory")
; #define PG8_WAIT_L(n) asm volatile("s_waitcnt lgkmcnt(" #n ")" ::: "memory")
; template <int MODE>
; __device__ __forceinline__ void gemm_phase(LAS unsigned char* lds, const Params& p, int l, int single) {
;     ...
;         for (int t = 0; t < nt; t += 2) {
;             const bool last = (t == nt - 2);
;             const char* a1 = cA + (size_t)(t + 1) * kstep;
;             const char* a2 = last ? nA : cA + (size_t)(t + 2) * kstep; const char* b2 = last ? nB : cB + (size_t)(t + 2) * kstep;
;             const char* a3 = a2 + kstep; const char* b3 = b2 + kstep;
;             PG8_LDB(B0, 0, 0); PG8_SCHED; PG8_LDA(At, 0, 0); PG8_STAGE(PG8_SA(1, 1), a1 + hstep, voffA);
;             PG8_WAIT_L(8); PG8_BAR; PG8_WAIT_L(0); PG8_MMA(0, 0, At, B0); PG8_BAR; PG8_SCHED;
;             PG8_LDB(B1, 0, 1); PG8_STAGE(PG8_SB(0, 0), b2, voffB);
;             PG8_BAR; PG8_WAIT_L(0); PG8_MMA(0, 1, At, B1); PG8_BAR;
;             PG8_LDA(At, 0, 1); PG8_STAGE(PG8_SA(0, 0), a2, voffA);
;             PG8_BAR; PG8_WAIT_L(0); PG8_MMA(1, 0, At, B0); PG8_BAR; PG8_SCHED;
;             PG8_STAGE(PG8_SB(0, 1), b2 + hstep, voffB);
;             PG8_WAIT_V(6); PG8_BAR; PG8_MMA(1, 1, At, B1); PG8_BAR;
;             PG8_LDB(B0, 1, 0); PG8_SCHED; PG8_LDA(At, 1, 0); PG8_STAGE(PG8_SA(0, 1), a2 + hstep, voffA);
;             PG8_WAIT_L(8); PG8_BAR; PG8_WAIT_L(0); PG8_MMA(0, 0, At, B0); PG8_BAR; PG8_SCHED;
;             PG8_LDB(B1, 1, 1); PG8_STAGE(PG8_SB(1, 0), b3, voffB);
;             PG8_BAR; PG8_WAIT_L(0); PG8_MMA(0, 1, At, B1); PG8_BAR;
;             PG8_LDA(At, 1, 1); PG8_STAGE(PG8_SA(1, 0), a3, voffA);
;             PG8_BAR; PG8_WAIT_L(0); PG8_MMA(1, 0, At, B0); PG8_BAR; PG8_SCHED;
;             PG8_STAGE(PG8_SB(1, 1), b3 + hstep, voffB);
;             PG8_WAIT_V(6); PG8_BAR; PG8_MMA(1, 1, At, B1); PG8_BAR;
.LBB0_840:
	s_add_u32 s20, s18, 0xfff80080
	s_addc_u32 s21, s19, -1
	s_add_i32 s96, 0, 0x10000
	v_add_u32_e32 v142, s96, v162
	ds_read_b128 v[156:159], v142
	ds_read_b128 v[164:167], v142 offset:1024
	ds_read_b128 v[168:171], v142 offset:2048
	ds_read_b128 v[172:175], v142 offset:3072
	s_cmp_eq_u32 s85, 28
	s_cselect_b32 vcc_hi, s11, s21
	s_cselect_b32 vcc_lo, s13, s20
	s_cselect_b32 s21, s15, s84
	s_cselect_b32 s20, s24, s33
	v_lshl_add_u64 v[142:143], s[18:19], 0, v[152:153]
	s_add_i32 m0, s25, 0xc000
	ds_read_b128 v[176:179], v163
	ds_read_b128 v[180:183], v163 offset:1024
	ds_read_b128 v[184:187], v163 offset:2048
	ds_read_b128 v[188:191], v163 offset:3072
	ds_read_b128 v[192:195], v163 offset:4096
	ds_read_b128 v[196:199], v163 offset:5120
	ds_read_b128 v[208:211], v163 offset:6144
	ds_read_b128 v[212:215], v163 offset:7168
	global_load_lds_dwordx4 v[142:143], off
	v_lshl_add_u64 v[142:143], s[18:19], 0, v[154:155]
	s_add_i32 m0, s25, 0xe000
	s_nop 0
	global_load_lds_dwordx4 v[142:143], off
	s_waitcnt lgkmcnt(8)
	s_barrier
	s_waitcnt lgkmcnt(0)
	s_setprio 1
	s_waitcnt lgkmcnt(0)
	v_mfma_f32_16x16x32_bf16 v[126:129], v[156:159], v[176:179], v[126:129]
	v_mfma_f32_16x16x32_bf16 v[122:125], v[168:171], v[176:179], v[122:125]
	v_mfma_f32_16x16x32_bf16 v[110:113], v[156:159], v[184:187], v[110:113]
	v_mfma_f32_16x16x32_bf16 v[106:109], v[168:171], v[184:187], v[106:109]
	v_mfma_f32_16x16x32_bf16 v[94:97], v[156:159], v[192:195], v[94:97]
	v_mfma_f32_16x16x32_bf16 v[90:93], v[168:171], v[192:195], v[90:93]
	v_mfma_f32_16x16x32_bf16 v[78:81], v[156:159], v[208:211], v[78:81]
	v_mfma_f32_16x16x32_bf16 v[74:77], v[168:171], v[208:211], v[74:77]
	v_mfma_f32_16x16x32_bf16 v[126:129], v[164:167], v[180:183], v[126:129]
	v_mfma_f32_16x16x32_bf16 v[122:125], v[172:175], v[180:183], v[122:125]
	v_mfma_f32_16x16x32_bf16 v[110:113], v[164:167], v[188:191], v[110:113]
	v_mfma_f32_16x16x32_bf16 v[106:109], v[172:175], v[188:191], v[106:109]
	v_mfma_f32_16x16x32_bf16 v[94:97], v[164:167], v[196:199], v[94:97]
	v_mfma_f32_16x16x32_bf16 v[90:93], v[172:175], v[196:199], v[90:93]
	v_mfma_f32_16x16x32_bf16 v[78:81], v[164:167], v[212:215], v[78:81]
	v_mfma_f32_16x16x32_bf16 v[74:77], v[172:175], v[212:215], v[74:77]
	s_setprio 0
	s_barrier
	s_add_i32 s22, 0, 0x14000
	v_add_u32_e32 v142, s22, v162
	s_add_i32 s96, s96, s23
	ds_read_b128 v[216:219], v142
	ds_read_b128 v[220:223], v142 offset:1024
	ds_read_b128 v[224:227], v142 offset:2048
	ds_read_b128 v[228:231], v142 offset:3072
	v_lshl_add_u64 v[142:143], s[20:21], 0, v[0:1]
	s_mov_b32 m0, s96
	v_lshl_add_u64 v[160:161], s[20:21], 0, v[130:131]
	global_load_lds_dwordx4 v[142:143], off
	s_add_i32 m0, s96, 0x2000
	s_nop 0
	global_load_lds_dwordx4 v[160:161], off
	s_barrier
	s_waitcnt lgkmcnt(0)
	s_setprio 1
	s_waitcnt lgkmcnt(0)
	v_mfma_f32_16x16x32_bf16 v[118:121], v[216:219], v[176:179], v[118:121]
	v_mfma_f32_16x16x32_bf16 v[114:117], v[224:227], v[176:179], v[114:117]
	v_mfma_f32_16x16x32_bf16 v[102:105], v[216:219], v[184:187], v[102:105]
	v_mfma_f32_16x16x32_bf16 v[98:101], v[224:227], v[184:187], v[98:101]
	v_mfma_f32_16x16x32_bf16 v[86:89], v[216:219], v[192:195], v[86:89]
	v_mfma_f32_16x16x32_bf16 v[82:85], v[224:227], v[192:195], v[82:85]
	v_mfma_f32_16x16x32_bf16 v[70:73], v[216:219], v[208:211], v[70:73]
	v_mfma_f32_16x16x32_bf16 v[66:69], v[224:227], v[208:211], v[66:69]
	v_mfma_f32_16x16x32_bf16 v[118:121], v[220:223], v[180:183], v[118:121]
	v_mfma_f32_16x16x32_bf16 v[114:117], v[228:231], v[180:183], v[114:117]
	v_mfma_f32_16x16x32_bf16 v[102:105], v[220:223], v[188:191], v[102:105]
	v_mfma_f32_16x16x32_bf16 v[98:101], v[228:231], v[188:191], v[98:101]
	v_mfma_f32_16x16x32_bf16 v[86:89], v[220:223], v[196:199], v[86:89]
	v_mfma_f32_16x16x32_bf16 v[82:85], v[228:231], v[196:199], v[82:85]
	v_mfma_f32_16x16x32_bf16 v[70:73], v[220:223], v[212:215], v[70:73]
	v_mfma_f32_16x16x32_bf16 v[66:69], v[228:231], v[212:215], v[66:69]
	s_setprio 0
	s_mov_b32 m0, s25
	v_lshl_add_u64 v[232:233], vcc, 0, v[146:147]
	s_barrier
	ds_read_b128 v[176:179], v163 offset:16384
	ds_read_b128 v[180:183], v163 offset:17408
	ds_read_b128 v[184:187], v163 offset:18432
	ds_read_b128 v[188:191], v163 offset:19456
	ds_read_b128 v[192:195], v163 offset:20480
	ds_read_b128 v[196:199], v163 offset:21504
	ds_read_b128 v[208:211], v163 offset:22528
	ds_read_b128 v[212:215], v163 offset:23552
	global_load_lds_dwordx4 v[232:233], off
	v_lshl_add_u64 v[234:235], vcc, 0, v[132:133]
	s_mov_b32 m0, s28
	s_nop 0
	global_load_lds_dwordx4 v[234:235], off
	s_barrier
	s_waitcnt lgkmcnt(0)
	s_setprio 1
	s_waitcnt lgkmcnt(0)
	v_mfma_f32_16x16x32_bf16 v[62:65], v[156:159], v[176:179], v[62:65]
	v_mfma_f32_16x16x32_bf16 v[58:61], v[168:171], v[176:179], v[58:61]
	v_mfma_f32_16x16x32_bf16 v[46:49], v[156:159], v[184:187], v[46:49]
	v_mfma_f32_16x16x32_bf16 v[42:45], v[168:171], v[184:187], v[42:45]
	v_mfma_f32_16x16x32_bf16 v[30:33], v[156:159], v[192:195], v[30:33]
	v_mfma_f32_16x16x32_bf16 v[26:29], v[168:171], v[192:195], v[26:29]
	v_mfma_f32_16x16x32_bf16 v[14:17], v[156:159], v[208:211], v[14:17]
	v_mfma_f32_16x16x32_bf16 v[10:13], v[168:171], v[208:211], v[10:13]
	v_mfma_f32_16x16x32_bf16 v[62:65], v[164:167], v[180:183], v[62:65]
	v_mfma_f32_16x16x32_bf16 v[58:61], v[172:175], v[180:183], v[58:61]
	v_mfma_f32_16x16x32_bf16 v[46:49], v[164:167], v[188:191], v[46:49]
	v_mfma_f32_16x16x32_bf16 v[42:45], v[172:175], v[188:191], v[42:45]
	v_mfma_f32_16x16x32_bf16 v[30:33], v[164:167], v[196:199], v[30:33]
	v_mfma_f32_16x16x32_bf16 v[26:29], v[172:175], v[196:199], v[26:29]
	v_mfma_f32_16x16x32_bf16 v[14:17], v[164:167], v[212:215], v[14:17]
	v_mfma_f32_16x16x32_bf16 v[10:13], v[172:175], v[212:215], v[10:13]
	s_setprio 0
	s_barrier
; #define PG8_STAGE(bufoff, gbase, voff) do { _Pragma("unroll") for (int _i = 0; _i < 2; ++_i) \
;         __builtin_amdgcn_global_load_lds((const unsigned*)((const char*)(gbase) + (voff)[_i]), (LAS unsigned*)(lds + (bufoff) + ldsw + _i * 8192), 16, 0, 0); } while (0)
; #define PG8_LDA(dst, b, h) do { _Pragma("unroll") for (int m = 0; m < 4; ++m) _Pragma("unroll") for (int k = 0; k < 2; ++k) dst[m][k] = *(const LAS bf16x8*)(lds + PG8_SA(b, h) + aoff + m * 2048 + k * 1024); } while (0)
; #define PG8_LDB(dst, b, h) do { _Pragma("unroll") for (int n = 0; n < 2; ++n) _Pragma("unroll") for (int k = 0; k < 2; ++k) dst[n][k] = *(const LAS bf16x8*)(lds + PG8_SB(b, h) + boff + n * 2048 + k * 1024); } while (0)
; #define PG8_WAIT_V(n) asm volatile("s_waitcnt vmcnt(" #n ")" ::: "memory")
; #define PG8_WAIT_L(n) asm volatile("s_waitcnt lgkmcnt(" #n ")" ::: "memory")
; #define PG8_BAR __builtin_amdgcn_s_barrier()
; #define PG8_SCHED __builtin_amdgcn_sched_barrier(0)
; template <int MODE>
; __device__ __forceinline__ void gemm_phase(LAS unsigned char* lds, const Params& p, int l, int single) {
;     ...
;             PG8_LDB(B0, 0, 0); PG8_SCHED; PG8_LDA(At, 0, 0); PG8_STAGE(PG8_SA(1, 1), a1 + hstep, voffA);
;             PG8_WAIT_L(8); PG8_BAR; PG8_WAIT_L(0); PG8_MMA(0, 0, At, B0); PG8_BAR; PG8_SCHED;
;             PG8_LDB(B1, 0, 1); PG8_STAGE(PG8_SB(0, 0), b2, voffB);
;             PG8_BAR; PG8_WAIT_L(0); PG8_MMA(0, 1, At, B1); PG8_BAR;
;             PG8_LDA(At, 0, 1); PG8_STAGE(PG8_SA(0, 0), a2, voffA);
;             PG8_BAR; PG8_WAIT_L(0); PG8_MMA(1, 0, At, B0); PG8_BAR; PG8_SCHED;
;             PG8_STAGE(PG8_SB(0, 1), b2 + hstep, voffB);
;             PG8_WAIT_V(6); PG8_BAR; PG8_MMA(1, 1, At, B1); PG8_BAR;
;             PG8_LDB(B0, 1, 0); PG8_SCHED; PG8_LDA(At, 1, 0); PG8_STAGE(PG8_SA(0, 1), a2 + hstep, voffA);
;             PG8_WAIT_L(8); PG8_BAR; PG8_WAIT_L(0); PG8_MMA(0, 0, At, B0); PG8_BAR; PG8_SCHED;
;             PG8_LDB(B1, 1, 1); PG8_STAGE(PG8_SB(1, 0), b3, voffB);
;             PG8_BAR; PG8_WAIT_L(0); PG8_MMA(0, 1, At, B1); PG8_BAR;
;             PG8_LDA(At, 1, 1); PG8_STAGE(PG8_SA(1, 0), a3, voffA);
;             PG8_BAR; PG8_WAIT_L(0); PG8_MMA(1, 0, At, B0); PG8_BAR; PG8_SCHED;
;             PG8_STAGE(PG8_SB(1, 1), b3 + hstep, voffB);
;             PG8_WAIT_V(6); PG8_BAR; PG8_MMA(1, 1, At, B1); PG8_BAR;
	s_add_u32 s96, s20, 0x80000
	s_addc_u32 s97, s21, 0
	s_add_i32 s22, s22, s23
	v_lshl_add_u64 v[156:157], s[96:97], 0, v[0:1]
	s_mov_b32 m0, s22
	s_nop 0
	global_load_lds_dwordx4 v[156:157], off
	v_lshl_add_u64 v[156:157], s[96:97], 0, v[130:131]
	s_add_i32 m0, s22, 0x2000
	s_nop 0
	global_load_lds_dwordx4 v[156:157], off
	s_waitcnt vmcnt(6)
	s_barrier
	s_setprio 1
	v_mfma_f32_16x16x32_bf16 v[54:57], v[216:219], v[176:179], v[54:57]
	v_mfma_f32_16x16x32_bf16 v[50:53], v[224:227], v[176:179], v[50:53]
	v_mfma_f32_16x16x32_bf16 v[38:41], v[216:219], v[184:187], v[38:41]
	v_mfma_f32_16x16x32_bf16 v[34:37], v[224:227], v[184:187], v[34:37]
	v_mfma_f32_16x16x32_bf16 v[22:25], v[216:219], v[192:195], v[22:25]
	v_mfma_f32_16x16x32_bf16 v[18:21], v[224:227], v[192:195], v[18:21]
	v_mfma_f32_16x16x32_bf16 v[6:9], v[216:219], v[208:211], v[6:9]
	v_mfma_f32_16x16x32_bf16 v[2:5], v[224:227], v[208:211], v[2:5]
	v_mfma_f32_16x16x32_bf16 v[54:57], v[220:223], v[180:183], v[54:57]
	v_mfma_f32_16x16x32_bf16 v[50:53], v[228:231], v[180:183], v[50:53]
	v_mfma_f32_16x16x32_bf16 v[38:41], v[220:223], v[188:191], v[38:41]
	v_mfma_f32_16x16x32_bf16 v[34:37], v[228:231], v[188:191], v[34:37]
	v_mfma_f32_16x16x32_bf16 v[22:25], v[220:223], v[196:199], v[22:25]
	v_mfma_f32_16x16x32_bf16 v[18:21], v[228:231], v[196:199], v[18:21]
	v_mfma_f32_16x16x32_bf16 v[6:9], v[220:223], v[212:215], v[6:9]
	v_mfma_f32_16x16x32_bf16 v[2:5], v[228:231], v[212:215], v[2:5]
	s_setprio 0
	s_add_i32 s22, 0, 0x18000
	v_add_u32_e32 v172, s22, v162
	s_barrier
	ds_read_b128 v[156:159], v172
	ds_read_b128 v[164:167], v172 offset:1024
	ds_read_b128 v[168:171], v172 offset:2048
	ds_read_b128 v[172:175], v172 offset:3072
	s_add_u32 s96, vcc_lo, 0x80000
	s_addc_u32 s97, vcc_hi, 0
	s_mov_b32 m0, s29
	v_lshl_add_u64 v[216:217], s[96:97], 0, v[146:147]
	ds_read_b128 v[176:179], v163 offset:32768
	ds_read_b128 v[180:183], v163 offset:33792
	ds_read_b128 v[184:187], v163 offset:34816
	ds_read_b128 v[188:191], v163 offset:35840
	ds_read_b128 v[192:195], v163 offset:36864
	ds_read_b128 v[196:199], v163 offset:37888
	ds_read_b128 v[208:211], v163 offset:38912
	ds_read_b128 v[212:215], v163 offset:39936
	global_load_lds_dwordx4 v[216:217], off
	v_lshl_add_u64 v[216:217], s[96:97], 0, v[132:133]
	s_mov_b32 m0, s76
	s_nop 0
	global_load_lds_dwordx4 v[216:217], off
	s_waitcnt lgkmcnt(8)
	s_barrier
	s_waitcnt lgkmcnt(0)
	s_setprio 1
	s_waitcnt lgkmcnt(0)
	v_mfma_f32_16x16x32_bf16 v[126:129], v[156:159], v[176:179], v[126:129]
	v_mfma_f32_16x16x32_bf16 v[122:125], v[168:171], v[176:179], v[122:125]
	v_mfma_f32_16x16x32_bf16 v[110:113], v[156:159], v[184:187], v[110:113]
	v_mfma_f32_16x16x32_bf16 v[106:109], v[168:171], v[184:187], v[106:109]
	v_mfma_f32_16x16x32_bf16 v[94:97], v[156:159], v[192:195], v[94:97]
	v_mfma_f32_16x16x32_bf16 v[90:93], v[168:171], v[192:195], v[90:93]
	v_mfma_f32_16x16x32_bf16 v[78:81], v[156:159], v[208:211], v[78:81]
	v_mfma_f32_16x16x32_bf16 v[74:77], v[168:171], v[208:211], v[74:77]
	v_mfma_f32_16x16x32_bf16 v[126:129], v[164:167], v[180:183], v[126:129]
	v_mfma_f32_16x16x32_bf16 v[122:125], v[172:175], v[180:183], v[122:125]
	v_mfma_f32_16x16x32_bf16 v[110:113], v[164:167], v[188:191], v[110:113]
	v_mfma_f32_16x16x32_bf16 v[106:109], v[172:175], v[188:191], v[106:109]
	v_mfma_f32_16x16x32_bf16 v[94:97], v[164:167], v[196:199], v[94:97]
	v_mfma_f32_16x16x32_bf16 v[90:93], v[172:175], v[196:199], v[90:93]
	v_mfma_f32_16x16x32_bf16 v[78:81], v[164:167], v[212:215], v[78:81]
	v_mfma_f32_16x16x32_bf16 v[74:77], v[172:175], v[212:215], v[74:77]
	s_setprio 0
	s_barrier
	s_add_i32 s96, 0, 0x1c000
	s_add_i32 s22, s22, s23
	v_add_u32_e32 v207, s96, v162
	v_lshl_add_u64 v[142:143], v[142:143], 0, s[94:95]
	s_mov_b32 m0, s22
	ds_read_b128 v[216:219], v207
	ds_read_b128 v[220:223], v207 offset:1024
	ds_read_b128 v[224:227], v207 offset:2048
	ds_read_b128 v[228:231], v207 offset:3072
	global_load_lds_dwordx4 v[142:143], off
	v_lshl_add_u64 v[142:143], v[160:161], 0, s[94:95]
	s_add_i32 m0, s22, 0x2000
	s_nop 0
	global_load_lds_dwordx4 v[142:143], off
	s_barrier
	s_waitcnt lgkmcnt(0)
	s_setprio 1
	s_waitcnt lgkmcnt(0)
	v_mfma_f32_16x16x32_bf16 v[118:121], v[216:219], v[176:179], v[118:121]
	v_mfma_f32_16x16x32_bf16 v[114:117], v[224:227], v[176:179], v[114:117]
	v_mfma_f32_16x16x32_bf16 v[102:105], v[216:219], v[184:187], v[102:105]
	v_mfma_f32_16x16x32_bf16 v[98:101], v[224:227], v[184:187], v[98:101]
	v_mfma_f32_16x16x32_bf16 v[86:89], v[216:219], v[192:195], v[86:89]
	v_mfma_f32_16x16x32_bf16 v[82:85], v[224:227], v[192:195], v[82:85]
	v_mfma_f32_16x16x32_bf16 v[70:73], v[216:219], v[208:211], v[70:73]
	v_mfma_f32_16x16x32_bf16 v[66:69], v[224:227], v[208:211], v[66:69]
	v_mfma_f32_16x16x32_bf16 v[118:121], v[220:223], v[180:183], v[118:121]
	v_mfma_f32_16x16x32_bf16 v[114:117], v[228:231], v[180:183], v[114:117]
	v_mfma_f32_16x16x32_bf16 v[102:105], v[220:223], v[188:191], v[102:105]
	v_mfma_f32_16x16x32_bf16 v[98:101], v[228:231], v[188:191], v[98:101]
	v_mfma_f32_16x16x32_bf16 v[86:89], v[220:223], v[196:199], v[86:89]
	v_mfma_f32_16x16x32_bf16 v[82:85], v[228:231], v[196:199], v[82:85]
	v_mfma_f32_16x16x32_bf16 v[70:73], v[220:223], v[212:215], v[70:73]
	v_mfma_f32_16x16x32_bf16 v[66:69], v[228:231], v[212:215], v[66:69]
	s_setprio 0
	s_mov_b32 m0, s90
	v_lshl_add_u64 v[142:143], v[232:233], 0, s[94:95]
	s_barrier
	ds_read_b128 v[176:179], v163 offset:49152
	ds_read_b128 v[180:183], v163 offset:50176
	ds_read_b128 v[184:187], v163 offset:51200
	ds_read_b128 v[188:191], v163 offset:52224
	ds_read_b128 v[192:195], v163 offset:53248
	ds_read_b128 v[196:199], v163 offset:54272
	ds_read_b128 v[208:211], v163 offset:55296
	ds_read_b128 v[212:215], v163 offset:56320
	global_load_lds_dwordx4 v[142:143], off
	v_lshl_add_u64 v[142:143], v[234:235], 0, s[94:95]
	s_mov_b32 m0, s6
	s_nop 0
	global_load_lds_dwordx4 v[142:143], off
	s_barrier
; __device__ __forceinline__ float bflo(unsigned w) { return __uint_as_float(w << 16); }
; __device__ __forceinline__ float bfhi(unsigned w) { return __uint_as_float(w & 0xffff0000u); }
; #define PG8_STAGE(bufoff, gbase, voff) do { _Pragma("unroll") for (int _i = 0; _i < 2; ++_i) \
;         __builtin_amdgcn_global_load_lds((const unsigned*)((const char*)(gbase) + (voff)[_i]), (LAS unsigned*)(lds + (bufoff) + ldsw + _i * 8192), 16, 0, 0); } while (0)
; #define PG8_MMA(ai, bj, At, Bt) do { __builtin_amdgcn_s_setprio(1); _Pragma("unroll") for (int m = 0; m < 4; ++m) _Pragma("unroll") for (int n = 0; n < 2; ++n) _Pragma("unroll") for (int k = 0; k < 2; ++k) \
;         acc[ai][bj][m][n] = __builtin_amdgcn_mfma_f32_16x16x32_bf16(Bt[n][k], At[m][k], acc[ai][bj][m][n], 0, 0, 0); __builtin_amdgcn_s_setprio(0); } while (0)
; #define PG8_WAIT_V(n) asm volatile("s_waitcnt vmcnt(" #n ")" ::: "memory")
; template <int MODE>
; __device__ __forceinline__ void gemm_epilogue(const Params& p, int l, const f32x4 (&acc)[2][2][4][2], const Unit& u, int wr, int wc, int fr, int fq, const LAS float* rl, int pm0) {
;     ...
;         u16* xb = (u16*)(ws + WS_XB);
;         u64* ssn = (u64*)(ws + WS_SUMSQ) + (size_t)(l + 1) * T;
; #pragma unroll
;         for (int ai = 0; ai < 2; ++ai)
; #pragma unroll
;             for (int m = 0; m < 4; ++m) {
;                 const int tok = u.pm * 256 + 128 * ai + 64 * wr + 16 * m + fr;
;                 float part = 0.f;
; #pragma unroll
;                 for (int bj = 0; bj < 2; ++bj) {
;                     const size_t idx = (size_t)tok * 2048 + u.pn * 256 + 128 * bj + 32 * wc + 8 * fq;
;                     const u32x4 xw = *(const u32x4*)(xb + idx);
;                     f32x4 y0 = (f32x4){bflo(xw.x), bfhi(xw.x), bflo(xw.y), bfhi(xw.y)}, y1 = (f32x4){bflo(xw.z), bfhi(xw.z), bflo(xw.w), bfhi(xw.w)};
;                     y0 += acc[ai][bj][m][0]; y1 += acc[ai][bj][m][1];
; template <int MODE>
; __device__ __forceinline__ void gemm_phase(LAS unsigned char* lds, const Params& p, int l, int single) {
;     ...
;             PG8_BAR; PG8_WAIT_L(0); PG8_MMA(1, 0, At, B0); PG8_BAR; PG8_SCHED;
;             PG8_STAGE(PG8_SB(1, 1), b3 + hstep, voffB);
;             PG8_WAIT_V(6); PG8_BAR; PG8_MMA(1, 1, At, B1); PG8_BAR;
;         }
;         gemm_epilogue<MODE>(p, l, acc, cur, wr, wc, fr, fq, rl, pm0);
;         if (!has_next) break;
	s_waitcnt lgkmcnt(0)
	s_setprio 1
	s_waitcnt lgkmcnt(0)
	v_mfma_f32_16x16x32_bf16 v[62:65], v[156:159], v[176:179], v[62:65]
	v_mfma_f32_16x16x32_bf16 v[58:61], v[168:171], v[176:179], v[58:61]
	v_mfma_f32_16x16x32_bf16 v[46:49], v[156:159], v[184:187], v[46:49]
	v_mfma_f32_16x16x32_bf16 v[42:45], v[168:171], v[184:187], v[42:45]
	v_mfma_f32_16x16x32_bf16 v[30:33], v[156:159], v[192:195], v[30:33]
	v_mfma_f32_16x16x32_bf16 v[26:29], v[168:171], v[192:195], v[26:29]
	v_mfma_f32_16x16x32_bf16 v[14:17], v[156:159], v[208:211], v[14:17]
	v_mfma_f32_16x16x32_bf16 v[10:13], v[168:171], v[208:211], v[10:13]
	v_mfma_f32_16x16x32_bf16 v[62:65], v[164:167], v[180:183], v[62:65]
	v_mfma_f32_16x16x32_bf16 v[58:61], v[172:175], v[180:183], v[58:61]
	v_mfma_f32_16x16x32_bf16 v[46:49], v[164:167], v[188:191], v[46:49]
	v_mfma_f32_16x16x32_bf16 v[42:45], v[172:175], v[188:191], v[42:45]
	v_mfma_f32_16x16x32_bf16 v[30:33], v[164:167], v[196:199], v[30:33]
	v_mfma_f32_16x16x32_bf16 v[26:29], v[172:175], v[196:199], v[26:29]
	v_mfma_f32_16x16x32_bf16 v[14:17], v[164:167], v[212:215], v[14:17]
	v_mfma_f32_16x16x32_bf16 v[10:13], v[172:175], v[212:215], v[10:13]
	s_setprio 0
	s_barrier
	s_add_u32 s20, s20, 0x80080
	s_addc_u32 s21, s21, 0
	s_add_i32 s22, s96, s23
	v_lshl_add_u64 v[142:143], s[20:21], 0, v[0:1]
	s_mov_b32 m0, s22
	s_nop 0
	global_load_lds_dwordx4 v[142:143], off
	v_lshl_add_u64 v[142:143], s[20:21], 0, v[130:131]
	s_add_i32 m0, s22, 0x2000
	s_nop 0
	global_load_lds_dwordx4 v[142:143], off
	s_waitcnt vmcnt(6)
	s_barrier
	s_setprio 1
	v_mfma_f32_16x16x32_bf16 v[54:57], v[216:219], v[176:179], v[54:57]
	v_mfma_f32_16x16x32_bf16 v[50:53], v[224:227], v[176:179], v[50:53]
	v_mfma_f32_16x16x32_bf16 v[38:41], v[216:219], v[184:187], v[38:41]
	v_mfma_f32_16x16x32_bf16 v[34:37], v[224:227], v[184:187], v[34:37]
	v_mfma_f32_16x16x32_bf16 v[22:25], v[216:219], v[192:195], v[22:25]
	v_mfma_f32_16x16x32_bf16 v[18:21], v[224:227], v[192:195], v[18:21]
	v_mfma_f32_16x16x32_bf16 v[6:9], v[216:219], v[208:211], v[6:9]
	v_mfma_f32_16x16x32_bf16 v[2:5], v[224:227], v[208:211], v[2:5]
	v_mfma_f32_16x16x32_bf16 v[54:57], v[220:223], v[180:183], v[54:57]
	v_mfma_f32_16x16x32_bf16 v[50:53], v[228:231], v[180:183], v[50:53]
	v_mfma_f32_16x16x32_bf16 v[38:41], v[220:223], v[188:191], v[38:41]
	v_mfma_f32_16x16x32_bf16 v[34:37], v[228:231], v[188:191], v[34:37]
	v_mfma_f32_16x16x32_bf16 v[22:25], v[220:223], v[196:199], v[22:25]
	v_mfma_f32_16x16x32_bf16 v[18:21], v[228:231], v[196:199], v[18:21]
	v_mfma_f32_16x16x32_bf16 v[6:9], v[220:223], v[212:215], v[6:9]
	v_mfma_f32_16x16x32_bf16 v[2:5], v[228:231], v[212:215], v[2:5]
	s_setprio 0
	s_add_i32 s85, s85, 2
	s_add_u32 s18, s18, 0x100
	s_addc_u32 s19, s19, 0
	s_add_u32 s33, s33, 0x100
	s_addc_u32 s84, s84, 0
	s_cmp_gt_u32 s85, 29
	s_barrier
	s_cbranch_scc0 .LBB0_840
	v_lshl_add_u32 v158, s10, 8, v149
	s_lshl_b32 s10, s2, 8
	s_ashr_i32 s11, s10, 31
	v_ashrrev_i32_e32 v159, 31, v158
	v_lshl_add_u64 v[156:157], s[10:11], 1, v[150:151]
	v_mov_b32_e32 v178, v158
	v_ashrrev_i32_e32 v179, 31, v178
	v_lshlrev_b64 v[178:179], 12, v[178:179]
	v_lshl_add_u64 v[178:179], v[156:157], 0, v[178:179]
	global_load_dwordx4 v[174:177], v[178:179], off
	global_load_dwordx4 v[178:181], v[178:179], off offset:256
	v_add_u32_e32 v186, 0x10, v158
	v_ashrrev_i32_e32 v187, 31, v186
	v_lshlrev_b64 v[186:187], 12, v[186:187]
	v_lshl_add_u64 v[186:187], v[156:157], 0, v[186:187]
	global_load_dwordx4 v[182:185], v[186:187], off
	global_load_dwordx4 v[186:189], v[186:187], off offset:256
	v_add_u32_e32 v194, 0x20, v158
	v_ashrrev_i32_e32 v195, 31, v194
	v_lshlrev_b64 v[194:195], 12, v[194:195]
	v_lshl_add_u64 v[194:195], v[156:157], 0, v[194:195]
	global_load_dwordx4 v[190:193], v[194:195], off
	global_load_dwordx4 v[194:197], v[194:195], off offset:256
	v_add_u32_e32 v212, 0x30, v158
	v_ashrrev_i32_e32 v213, 31, v212
	v_lshlrev_b64 v[212:213], 12, v[212:213]
	v_lshl_add_u64 v[212:213], v[156:157], 0, v[212:213]
	global_load_dwordx4 v[208:211], v[212:213], off
	global_load_dwordx4 v[212:215], v[212:213], off offset:256
	v_add_u32_e32 v220, 0x80, v158
	v_ashrrev_i32_e32 v221, 31, v220
	v_lshlrev_b64 v[220:221], 12, v[220:221]
	v_lshl_add_u64 v[220:221], v[156:157], 0, v[220:221]
	global_load_dwordx4 v[216:219], v[220:221], off
	global_load_dwordx4 v[220:223], v[220:221], off offset:256
	v_add_u32_e32 v228, 0x90, v158
	v_ashrrev_i32_e32 v229, 31, v228
	v_lshlrev_b64 v[228:229], 12, v[228:229]
	v_lshl_add_u64 v[228:229], v[156:157], 0, v[228:229]
	global_load_dwordx4 v[224:227], v[228:229], off
	global_load_dwordx4 v[228:231], v[228:229], off offset:256
	v_lshlrev_b64 v[142:143], 12, v[158:159]
	v_lshl_add_u64 v[168:169], v[156:157], 0, v[142:143]
	v_or_b32_e32 v160, s10, v148
	v_mov_b32_e32 v161, s11
	v_add_u32_e32 v172, 0x10800000, v142
	v_lshlrev_b64 v[160:161], 1, v[160:161]
	v_add_u32_e32 v161, v172, v160
	v_readlane_b32 s10, v252, 45
	v_readlane_b32 s11, v252, 46
	s_waitcnt vmcnt(11)
; __device__ __forceinline__ unsigned cvt_pk_bf16(float lo, float hi) { unsigned r; asm("v_cvt_pk_bf16_f32 %0, %1, %2" : "=v"(r) : "v"(lo), "v"(hi)); return r; }
; __device__ __forceinline__ float bflo(unsigned w) { return __uint_as_float(w << 16); }
; __device__ __forceinline__ float bfhi(unsigned w) { return __uint_as_float(w & 0xffff0000u); }
; #define WT_STORE16(ptr, val) __builtin_amdgcn_raw_buffer_store_b128((val), wsr, (int)((const char*)(ptr) - (const char*)ws), 0, 16)
; template <int MODE>
; __device__ __forceinline__ void gemm_epilogue(const Params& p, int l, const f32x4 (&acc)[2][2][4][2], const Unit& u, int wr, int wc, int fr, int fq, const LAS float* rl, int pm0) {
;     ...
; #pragma unroll
;         for (int ai = 0; ai < 2; ++ai)
; #pragma unroll
;             for (int m = 0; m < 4; ++m) {
;                 const int tok = u.pm * 256 + 128 * ai + 64 * wr + 16 * m + fr;
;                 float part = 0.f;
; #pragma unroll
;                 for (int bj = 0; bj < 2; ++bj) {
;                     const size_t idx = (size_t)tok * 2048 + u.pn * 256 + 128 * bj + 32 * wc + 8 * fq;
;                     const u32x4 xw = *(const u32x4*)(xb + idx);
;                     f32x4 y0 = (f32x4){bflo(xw.x), bfhi(xw.x), bflo(xw.y), bfhi(xw.y)}, y1 = (f32x4){bflo(xw.z), bfhi(xw.z), bflo(xw.w), bfhi(xw.w)};
;                     y0 += acc[ai][bj][m][0]; y1 += acc[ai][bj][m][1];
;                     part += y0[0] * y0[0] + y0[1] * y0[1] + y0[2] * y0[2] + y0[3] * y0[3] + y1[0] * y1[0] + y1[1] * y1[1] + y1[2] * y1[2] + y1[3] * y1[3];
;                     u32x4 w; w.x = cvt_pk_bf16(y0[0], y0[1]); w.y = cvt_pk_bf16(y0[2], y0[3]); w.z = cvt_pk_bf16(y1[0], y1[1]); w.w = cvt_pk_bf16(y1[2], y1[3]);
;                     WT_STORE16(xb + idx, w);
;                 }
;                 part += __shfl_xor(part, 16); part += __shfl_xor(part, 32);
;                 if (fq == 0) atomicAdd(ssn + tok, (u64)(part * SS_SCALE));
;             }
	v_mov_b32_e32 v164, v174
	v_mov_b32_e32 v165, v175
	v_mov_b32_e32 v166, v176
	v_mov_b32_e32 v167, v177
	v_lshlrev_b32_e32 v142, 16, v164
	v_and_b32_e32 v143, 0xffff0000, v164
	v_lshlrev_b32_e32 v164, 16, v165
	v_and_b32_e32 v165, 0xffff0000, v165
	v_lshlrev_b32_e32 v170, 16, v166
	v_and_b32_e32 v171, 0xffff0000, v166
	v_lshlrev_b32_e32 v166, 16, v167
	v_and_b32_e32 v167, 0xffff0000, v167
	v_pk_add_f32 v[128:129], v[128:129], v[164:165]
	v_pk_add_f32 v[142:143], v[126:127], v[142:143]
	v_pk_add_f32 v[164:165], v[124:125], v[166:167]
	v_pk_add_f32 v[166:167], v[122:123], v[170:171]
	v_cvt_pk_bf16_f32 v122, v142, v143
	v_cvt_pk_bf16_f32 v123, v128, v129
	v_cvt_pk_bf16_f32 v125, v164, v165
	s_nop 0
	v_cvt_pk_bf16_f32 v124, v166, v167
	buffer_store_dwordx4 v[122:125], v161, s[60:63], 0 offen sc1
	v_xor_b32_e32 v161, 32, v205
	v_and_b32_e32 v123, 64, v205
	v_xor_b32_e32 v122, 16, v205
	v_add_u32_e32 v123, 64, v123
	v_cmp_lt_i32_e32 vcc, v122, v123
	s_nop 1
	v_cndmask_b32_e32 v122, v205, v122, vcc
	v_cmp_lt_i32_e32 vcc, v161, v123
	v_lshlrev_b32_e32 v122, 2, v122
	s_nop 0
	v_cndmask_b32_e32 v123, v205, v161, vcc
	v_mul_f32_e32 v161, v143, v143
	v_fmac_f32_e32 v161, v142, v142
	v_fmac_f32_e32 v161, v128, v128
	v_fmac_f32_e32 v161, v129, v129
	v_fmac_f32_e32 v161, v166, v166
	v_fmac_f32_e32 v161, v167, v167
	v_fmac_f32_e32 v161, v164, v164
	v_fmac_f32_e32 v161, v165, v165
	s_waitcnt vmcnt(11)
	v_mov_b32_e32 v124, v178
	v_mov_b32_e32 v125, v179
	v_mov_b32_e32 v126, v180
	v_mov_b32_e32 v127, v181
	v_add_u32_e32 v178, 0xa0, v158
	v_ashrrev_i32_e32 v179, 31, v178
	v_lshlrev_b64 v[178:179], 12, v[178:179]
	v_lshl_add_u64 v[178:179], v[156:157], 0, v[178:179]
	global_load_dwordx4 v[174:177], v[178:179], off
	global_load_dwordx4 v[178:181], v[178:179], off offset:256
	v_lshlrev_b32_e32 v128, 16, v124
	v_and_b32_e32 v129, 0xffff0000, v124
	v_lshlrev_b32_e32 v124, 16, v125
	v_and_b32_e32 v125, 0xffff0000, v125
	v_pk_add_f32 v[118:119], v[118:119], v[128:129]
	v_pk_add_f32 v[120:121], v[120:121], v[124:125]
	v_mul_f32_e32 v124, v119, v119
	v_fmac_f32_e32 v124, v118, v118
	v_lshlrev_b32_e32 v142, 16, v126
	v_and_b32_e32 v143, 0xffff0000, v126
	v_fmac_f32_e32 v124, v120, v120
	v_pk_add_f32 v[114:115], v[114:115], v[142:143]
	v_fmac_f32_e32 v124, v121, v121
	v_lshlrev_b32_e32 v126, 16, v127
	v_and_b32_e32 v127, 0xffff0000, v127
	v_fmac_f32_e32 v124, v114, v114
	v_pk_add_f32 v[116:117], v[116:117], v[126:127]
	v_fmac_f32_e32 v124, v115, v115
	v_fmac_f32_e32 v124, v116, v116
	v_fmac_f32_e32 v124, v117, v117
	v_add_f32_e32 v128, v161, v124
	ds_bpermute_b32 v129, v122, v128
	v_cvt_pk_bf16_f32 v124, v118, v119
	v_cvt_pk_bf16_f32 v127, v116, v117
	v_lshlrev_b32_e32 v117, 2, v123
	v_or_b32_e32 v116, 0x100, v160
	s_waitcnt lgkmcnt(0)
	v_add_f32_e32 v118, v128, v129
	ds_bpermute_b32 v119, v117, v118
	v_cvt_pk_bf16_f32 v126, v114, v115
	v_add_u32_e32 v114, v172, v116
	v_cvt_pk_bf16_f32 v125, v120, v121
	buffer_store_dwordx4 v[124:127], v114, s[60:63], 0 offen sc1
	v_lshl_add_u64 v[114:115], v[158:159], 3, s[10:11]
	s_and_saveexec_b64 s[18:19], s[38:39]
	s_cbranch_execz .LBB0_843
	s_waitcnt lgkmcnt(0)
	v_add_f32_e32 v118, v118, v119
	v_mul_f32_e32 v118, 0x49800000, v118
	v_trunc_f32_e32 v118, v118
	v_mul_f32_e32 v119, 0x2f800000, v118
	v_floor_f32_e32 v119, v119
	v_fmac_f32_e32 v118, 0xcf800000, v119
	v_cvt_u32_f32_e32 v118, v118
	v_cvt_u32_f32_e32 v119, v119
	global_atomic_add_x2 v[114:115], v[118:119], off
.LBB0_843:
	s_or_b64 exec, exec, s[18:19]
	v_or_b32_e32 v118, 16, v158
	s_waitcnt lgkmcnt(0)
	v_ashrrev_i32_e32 v119, 31, v118
	v_lshlrev_b64 v[118:119], 12, v[118:119]
	v_lshl_add_u64 v[124:125], v[156:157], 0, v[118:119]
	v_add_u32_e32 v123, 0x10800000, v118
	s_waitcnt vmcnt(13)
	v_mov_b32_e32 v118, v182
	v_mov_b32_e32 v119, v183
	v_mov_b32_e32 v120, v184
	v_mov_b32_e32 v121, v185
	v_lshlrev_b32_e32 v126, 16, v118
	v_and_b32_e32 v127, 0xffff0000, v118
	v_lshlrev_b32_e32 v118, 16, v119
	v_and_b32_e32 v119, 0xffff0000, v119
	v_lshlrev_b32_e32 v128, 16, v120
	v_and_b32_e32 v129, 0xffff0000, v120
	v_lshlrev_b32_e32 v120, 16, v121
	v_and_b32_e32 v121, 0xffff0000, v121
	v_pk_add_f32 v[110:111], v[110:111], v[126:127]
	v_pk_add_f32 v[112:113], v[112:113], v[118:119]
	v_pk_add_f32 v[118:119], v[108:109], v[120:121]
	v_mul_f32_e32 v120, v111, v111
	v_fmac_f32_e32 v120, v110, v110
	v_fmac_f32_e32 v120, v112, v112
	v_pk_add_f32 v[108:109], v[106:107], v[128:129]
	v_fmac_f32_e32 v120, v113, v113
	v_fmac_f32_e32 v120, v108, v108
	v_cvt_pk_bf16_f32 v106, v110, v111
	v_add_u32_e32 v110, v123, v160
	v_fmac_f32_e32 v120, v109, v109
	v_cvt_pk_bf16_f32 v107, v112, v113
	v_cvt_pk_bf16_f32 v108, v108, v109
	v_cvt_pk_bf16_f32 v109, v118, v119
	buffer_store_dwordx4 v[106:109], v110, s[60:63], 0 offen sc1
	v_fmac_f32_e32 v120, v118, v118
	v_fmac_f32_e32 v120, v119, v119
	s_waitcnt vmcnt(13)
	v_mov_b32_e32 v106, v186
	v_mov_b32_e32 v107, v187
	v_mov_b32_e32 v108, v188
	v_mov_b32_e32 v109, v189
	v_add_u32_e32 v186, 0xb0, v158
	v_ashrrev_i32_e32 v187, 31, v186
	v_lshlrev_b64 v[186:187], 12, v[186:187]
	v_lshl_add_u64 v[186:187], v[156:157], 0, v[186:187]
	global_load_dwordx4 v[182:185], v[186:187], off
	global_load_dwordx4 v[186:189], v[186:187], off offset:256
	v_lshlrev_b32_e32 v110, 16, v106
	v_and_b32_e32 v111, 0xffff0000, v106
	v_lshlrev_b32_e32 v106, 16, v107
	v_and_b32_e32 v107, 0xffff0000, v107
	v_lshlrev_b32_e32 v112, 16, v108
	v_and_b32_e32 v113, 0xffff0000, v108
	v_lshlrev_b32_e32 v108, 16, v109
	v_and_b32_e32 v109, 0xffff0000, v109
	v_pk_add_f32 v[102:103], v[102:103], v[110:111]
	v_pk_add_f32 v[104:105], v[104:105], v[106:107]
	v_pk_add_f32 v[106:107], v[100:101], v[108:109]
	v_pk_add_f32 v[100:101], v[98:99], v[112:113]
	v_mul_f32_e32 v98, v103, v103
	v_fmac_f32_e32 v98, v102, v102
	v_fmac_f32_e32 v98, v104, v104
	v_fmac_f32_e32 v98, v105, v105
	v_fmac_f32_e32 v98, v100, v100
	v_fmac_f32_e32 v98, v101, v101
	v_fmac_f32_e32 v98, v106, v106
	v_fmac_f32_e32 v98, v107, v107
	v_add_f32_e32 v108, v120, v98
	v_cvt_pk_bf16_f32 v98, v102, v103
	v_add_u32_e32 v102, v123, v116
	v_cvt_pk_bf16_f32 v99, v104, v105
	v_cvt_pk_bf16_f32 v100, v100, v101
	v_cvt_pk_bf16_f32 v101, v106, v107
	buffer_store_dwordx4 v[98:101], v102, s[60:63], 0 offen sc1
	ds_bpermute_b32 v98, v122, v108
	s_waitcnt lgkmcnt(0)
	v_add_f32_e32 v98, v108, v98
	ds_bpermute_b32 v99, v117, v98
	s_and_saveexec_b64 s[18:19], s[38:39]
	s_movk_i32 s33, 0x100
	s_mov_b32 s13, s0
	s_cbranch_execz .LBB0_845
	s_waitcnt lgkmcnt(0)
	v_add_f32_e32 v98, v98, v99
	v_mul_f32_e32 v98, 0x49800000, v98
	v_trunc_f32_e32 v98, v98
	v_mul_f32_e32 v99, 0x2f800000, v98
	v_floor_f32_e32 v99, v99
	v_fmac_f32_e32 v98, 0xcf800000, v99
	v_cvt_u32_f32_e32 v98, v98
	v_cvt_u32_f32_e32 v99, v99
	global_atomic_add_x2 v[114:115], v[98:99], off offset:128
; __device__ __forceinline__ unsigned cvt_pk_bf16(float lo, float hi) { unsigned r; asm("v_cvt_pk_bf16_f32 %0, %1, %2" : "=v"(r) : "v"(lo), "v"(hi)); return r; }
; __device__ __forceinline__ float bflo(unsigned w) { return __uint_as_float(w << 16); }
; __device__ __forceinline__ float bfhi(unsigned w) { return __uint_as_float(w & 0xffff0000u); }
; #define WT_STORE16(ptr, val) __builtin_amdgcn_raw_buffer_store_b128((val), wsr, (int)((const char*)(ptr) - (const char*)ws), 0, 16)
; template <int MODE>
; __device__ __forceinline__ void gemm_epilogue(const Params& p, int l, const f32x4 (&acc)[2][2][4][2], const Unit& u, int wr, int wc, int fr, int fq, const LAS float* rl, int pm0) {
;     ...
; #pragma unroll
;         for (int ai = 0; ai < 2; ++ai)
; #pragma unroll
;             for (int m = 0; m < 4; ++m) {
;                 const int tok = u.pm * 256 + 128 * ai + 64 * wr + 16 * m + fr;
;                 float part = 0.f;
; #pragma unroll
;                 for (int bj = 0; bj < 2; ++bj) {
;                     const size_t idx = (size_t)tok * 2048 + u.pn * 256 + 128 * bj + 32 * wc + 8 * fq;
;                     const u32x4 xw = *(const u32x4*)(xb + idx);
;                     f32x4 y0 = (f32x4){bflo(xw.x), bfhi(xw.x), bflo(xw.y), bfhi(xw.y)}, y1 = (f32x4){bflo(xw.z), bfhi(xw.z), bflo(xw.w), bfhi(xw.w)};
;                     y0 += acc[ai][bj][m][0]; y1 += acc[ai][bj][m][1];
;                     part += y0[0] * y0[0] + y0[1] * y0[1] + y0[2] * y0[2] + y0[3] * y0[3] + y1[0] * y1[0] + y1[1] * y1[1] + y1[2] * y1[2] + y1[3] * y1[3];
;                     u32x4 w; w.x = cvt_pk_bf16(y0[0], y0[1]); w.y = cvt_pk_bf16(y0[2], y0[3]); w.z = cvt_pk_bf16(y1[0], y1[1]); w.w = cvt_pk_bf16(y1[2], y1[3]);
;                     WT_STORE16(xb + idx, w);
;                 }
;                 part += __shfl_xor(part, 16); part += __shfl_xor(part, 32);
;                 if (fq == 0) atomicAdd(ssn + tok, (u64)(part * SS_SCALE));
;             }
.LBB0_845:
	s_or_b64 exec, exec, s[18:19]
	v_or_b32_e32 v98, 32, v158
	s_waitcnt lgkmcnt(0)
	v_ashrrev_i32_e32 v99, 31, v98
	v_lshlrev_b64 v[98:99], 12, v[98:99]
	v_lshl_add_u64 v[102:103], v[156:157], 0, v[98:99]
	v_add_u32_e32 v108, 0x10800000, v98
	s_waitcnt vmcnt(15)
	v_mov_b32_e32 v98, v190
	v_mov_b32_e32 v99, v191
	v_mov_b32_e32 v100, v192
	v_mov_b32_e32 v101, v193
	v_lshlrev_b32_e32 v104, 16, v98
	v_and_b32_e32 v105, 0xffff0000, v98
	v_lshlrev_b32_e32 v98, 16, v99
	v_and_b32_e32 v99, 0xffff0000, v99
	v_lshlrev_b32_e32 v106, 16, v100
	v_and_b32_e32 v107, 0xffff0000, v100
	v_lshlrev_b32_e32 v100, 16, v101
	v_and_b32_e32 v101, 0xffff0000, v101
	v_pk_add_f32 v[94:95], v[94:95], v[104:105]
	v_pk_add_f32 v[96:97], v[96:97], v[98:99]
	v_pk_add_f32 v[98:99], v[92:93], v[100:101]
	v_mul_f32_e32 v100, v95, v95
	v_fmac_f32_e32 v100, v94, v94
	v_fmac_f32_e32 v100, v96, v96
	v_pk_add_f32 v[92:93], v[90:91], v[106:107]
	v_fmac_f32_e32 v100, v97, v97
	v_fmac_f32_e32 v100, v92, v92
	v_cvt_pk_bf16_f32 v90, v94, v95
	v_add_u32_e32 v94, v108, v160
	v_fmac_f32_e32 v100, v93, v93
	v_cvt_pk_bf16_f32 v91, v96, v97
	v_cvt_pk_bf16_f32 v92, v92, v93
	v_cvt_pk_bf16_f32 v93, v98, v99
	buffer_store_dwordx4 v[90:93], v94, s[60:63], 0 offen sc1
	v_fmac_f32_e32 v100, v98, v98
	v_fmac_f32_e32 v100, v99, v99
	s_waitcnt vmcnt(15)
	v_mov_b32_e32 v90, v194
	v_mov_b32_e32 v91, v195
	v_mov_b32_e32 v92, v196
	v_mov_b32_e32 v93, v197
	v_lshlrev_b32_e32 v94, 16, v90
	v_and_b32_e32 v95, 0xffff0000, v90
	v_lshlrev_b32_e32 v90, 16, v91
	v_and_b32_e32 v91, 0xffff0000, v91
	v_lshlrev_b32_e32 v96, 16, v92
	v_and_b32_e32 v97, 0xffff0000, v92
	v_lshlrev_b32_e32 v92, 16, v93
	v_and_b32_e32 v93, 0xffff0000, v93
	v_pk_add_f32 v[86:87], v[86:87], v[94:95]
	v_pk_add_f32 v[88:89], v[88:89], v[90:91]
	v_pk_add_f32 v[90:91], v[84:85], v[92:93]
	v_pk_add_f32 v[84:85], v[82:83], v[96:97]
	v_mul_f32_e32 v82, v87, v87
	v_fmac_f32_e32 v82, v86, v86
	v_fmac_f32_e32 v82, v88, v88
	v_fmac_f32_e32 v82, v89, v89
	v_fmac_f32_e32 v82, v84, v84
	v_fmac_f32_e32 v82, v85, v85
	v_fmac_f32_e32 v82, v90, v90
	v_fmac_f32_e32 v82, v91, v91
	v_add_f32_e32 v92, v100, v82
	v_cvt_pk_bf16_f32 v82, v86, v87
	v_add_u32_e32 v86, v108, v116
	v_cvt_pk_bf16_f32 v83, v88, v89
	v_cvt_pk_bf16_f32 v84, v84, v85
	v_cvt_pk_bf16_f32 v85, v90, v91
	buffer_store_dwordx4 v[82:85], v86, s[60:63], 0 offen sc1
	ds_bpermute_b32 v82, v122, v92
	s_waitcnt lgkmcnt(0)
	v_add_f32_e32 v82, v92, v82
	ds_bpermute_b32 v83, v117, v82
	s_and_saveexec_b64 s[18:19], s[38:39]
	s_cbranch_execz .LBB0_847
	s_waitcnt lgkmcnt(0)
	v_add_f32_e32 v82, v82, v83
	v_mul_f32_e32 v82, 0x49800000, v82
	v_trunc_f32_e32 v82, v82
	v_mul_f32_e32 v83, 0x2f800000, v82
	v_floor_f32_e32 v83, v83
	v_fmac_f32_e32 v82, 0xcf800000, v83
	v_cvt_u32_f32_e32 v82, v82
	v_cvt_u32_f32_e32 v83, v83
	global_atomic_add_x2 v[114:115], v[82:83], off offset:256
.LBB0_847:
	s_or_b64 exec, exec, s[18:19]
	v_or_b32_e32 v82, 48, v158
	s_waitcnt lgkmcnt(0)
	v_ashrrev_i32_e32 v83, 31, v82
	v_lshlrev_b64 v[82:83], 12, v[82:83]
	v_lshl_add_u64 v[86:87], v[156:157], 0, v[82:83]
	v_add_u32_e32 v92, 0x10800000, v82
	s_waitcnt vmcnt(15)
	v_mov_b32_e32 v82, v208
	v_mov_b32_e32 v83, v209
	v_mov_b32_e32 v84, v210
	v_mov_b32_e32 v85, v211
	v_lshlrev_b32_e32 v88, 16, v82
	v_and_b32_e32 v89, 0xffff0000, v82
	v_lshlrev_b32_e32 v82, 16, v83
	v_and_b32_e32 v83, 0xffff0000, v83
	v_lshlrev_b32_e32 v90, 16, v84
	v_and_b32_e32 v91, 0xffff0000, v84
	v_lshlrev_b32_e32 v84, 16, v85
	v_and_b32_e32 v85, 0xffff0000, v85
	v_pk_add_f32 v[78:79], v[78:79], v[88:89]
	v_pk_add_f32 v[80:81], v[80:81], v[82:83]
	v_pk_add_f32 v[82:83], v[76:77], v[84:85]
	v_mul_f32_e32 v84, v79, v79
	v_fmac_f32_e32 v84, v78, v78
	v_fmac_f32_e32 v84, v80, v80
	v_pk_add_f32 v[76:77], v[74:75], v[90:91]
	v_fmac_f32_e32 v84, v81, v81
	v_fmac_f32_e32 v84, v76, v76
	v_cvt_pk_bf16_f32 v74, v78, v79
	v_add_u32_e32 v78, v92, v160
	v_fmac_f32_e32 v84, v77, v77
	v_cvt_pk_bf16_f32 v75, v80, v81
	v_cvt_pk_bf16_f32 v76, v76, v77
	v_cvt_pk_bf16_f32 v77, v82, v83
	buffer_store_dwordx4 v[74:77], v78, s[60:63], 0 offen sc1
	v_fmac_f32_e32 v84, v82, v82
	v_fmac_f32_e32 v84, v83, v83
	s_waitcnt vmcnt(15)
	v_mov_b32_e32 v74, v212
	v_mov_b32_e32 v75, v213
	v_mov_b32_e32 v76, v214
	v_mov_b32_e32 v77, v215
	v_lshlrev_b32_e32 v78, 16, v74
	v_and_b32_e32 v79, 0xffff0000, v74
	v_lshlrev_b32_e32 v74, 16, v75
	v_and_b32_e32 v75, 0xffff0000, v75
	v_lshlrev_b32_e32 v80, 16, v76
	v_and_b32_e32 v81, 0xffff0000, v76
	v_lshlrev_b32_e32 v76, 16, v77
	v_and_b32_e32 v77, 0xffff0000, v77
	v_pk_add_f32 v[70:71], v[70:71], v[78:79]
	v_pk_add_f32 v[72:73], v[72:73], v[74:75]
	v_pk_add_f32 v[74:75], v[68:69], v[76:77]
	v_pk_add_f32 v[68:69], v[66:67], v[80:81]
	v_mul_f32_e32 v66, v71, v71
	v_fmac_f32_e32 v66, v70, v70
	v_fmac_f32_e32 v66, v72, v72
	v_fmac_f32_e32 v66, v73, v73
	v_fmac_f32_e32 v66, v68, v68
	v_fmac_f32_e32 v66, v69, v69
	v_fmac_f32_e32 v66, v74, v74
	v_fmac_f32_e32 v66, v75, v75
	v_add_f32_e32 v76, v84, v66
	v_cvt_pk_bf16_f32 v66, v70, v71
	v_add_u32_e32 v70, v92, v116
	v_cvt_pk_bf16_f32 v67, v72, v73
	v_cvt_pk_bf16_f32 v68, v68, v69
	v_cvt_pk_bf16_f32 v69, v74, v75
	buffer_store_dwordx4 v[66:69], v70, s[60:63], 0 offen sc1
	ds_bpermute_b32 v66, v122, v76
	s_waitcnt lgkmcnt(0)
	v_add_f32_e32 v66, v76, v66
	ds_bpermute_b32 v67, v117, v66
	s_and_saveexec_b64 s[18:19], s[38:39]
	v_readlane_b32 s84, v252, 43
	s_mov_b32 s96, 0x8400
	s_cbranch_execz .LBB0_849
	s_waitcnt lgkmcnt(0)
	v_add_f32_e32 v66, v66, v67
	v_mul_f32_e32 v66, 0x49800000, v66
	v_trunc_f32_e32 v66, v66
	v_mul_f32_e32 v67, 0x2f800000, v66
	v_floor_f32_e32 v67, v67
	v_fmac_f32_e32 v66, 0xcf800000, v67
	v_cvt_u32_f32_e32 v66, v66
	v_cvt_u32_f32_e32 v67, v67
	global_atomic_add_x2 v[114:115], v[66:67], off offset:384
; __device__ __forceinline__ unsigned cvt_pk_bf16(float lo, float hi) { unsigned r; asm("v_cvt_pk_bf16_f32 %0, %1, %2" : "=v"(r) : "v"(lo), "v"(hi)); return r; }
; __device__ __forceinline__ float bflo(unsigned w) { return __uint_as_float(w << 16); }
; __device__ __forceinline__ float bfhi(unsigned w) { return __uint_as_float(w & 0xffff0000u); }
; #define WT_STORE16(ptr, val) __builtin_amdgcn_raw_buffer_store_b128((val), wsr, (int)((const char*)(ptr) - (const char*)ws), 0, 16)
; template <int MODE>
; __device__ __forceinline__ void gemm_epilogue(const Params& p, int l, const f32x4 (&acc)[2][2][4][2], const Unit& u, int wr, int wc, int fr, int fq, const LAS float* rl, int pm0) {
;     ...
; #pragma unroll
;         for (int ai = 0; ai < 2; ++ai)
; #pragma unroll
;             for (int m = 0; m < 4; ++m) {
;                 const int tok = u.pm * 256 + 128 * ai + 64 * wr + 16 * m + fr;
;                 float part = 0.f;
; #pragma unroll
;                 for (int bj = 0; bj < 2; ++bj) {
;                     const size_t idx = (size_t)tok * 2048 + u.pn * 256 + 128 * bj + 32 * wc + 8 * fq;
;                     const u32x4 xw = *(const u32x4*)(xb + idx);
;                     f32x4 y0 = (f32x4){bflo(xw.x), bfhi(xw.x), bflo(xw.y), bfhi(xw.y)}, y1 = (f32x4){bflo(xw.z), bfhi(xw.z), bflo(xw.w), bfhi(xw.w)};
;                     y0 += acc[ai][bj][m][0]; y1 += acc[ai][bj][m][1];
;                     part += y0[0] * y0[0] + y0[1] * y0[1] + y0[2] * y0[2] + y0[3] * y0[3] + y1[0] * y1[0] + y1[1] * y1[1] + y1[2] * y1[2] + y1[3] * y1[3];
;                     u32x4 w; w.x = cvt_pk_bf16(y0[0], y0[1]); w.y = cvt_pk_bf16(y0[2], y0[3]); w.z = cvt_pk_bf16(y1[0], y1[1]); w.w = cvt_pk_bf16(y1[2], y1[3]);
;                     WT_STORE16(xb + idx, w);
;                 }
;                 part += __shfl_xor(part, 16); part += __shfl_xor(part, 32);
;                 if (fq == 0) atomicAdd(ssn + tok, (u64)(part * SS_SCALE));
;             }
.LBB0_849:
	s_or_b64 exec, exec, s[18:19]
	v_add_u32_e32 v66, 0x80, v158
	s_waitcnt lgkmcnt(0)
	v_ashrrev_i32_e32 v67, 31, v66
	v_lshlrev_b64 v[66:67], 12, v[66:67]
	v_lshl_add_u64 v[70:71], v[156:157], 0, v[66:67]
	v_add_u32_e32 v76, 0x10800000, v66
	s_waitcnt vmcnt(15)
	v_mov_b32_e32 v66, v216
	v_mov_b32_e32 v67, v217
	v_mov_b32_e32 v68, v218
	v_mov_b32_e32 v69, v219
	v_lshlrev_b32_e32 v72, 16, v66
	v_and_b32_e32 v73, 0xffff0000, v66
	v_lshlrev_b32_e32 v66, 16, v67
	v_and_b32_e32 v67, 0xffff0000, v67
	v_lshlrev_b32_e32 v74, 16, v68
	v_and_b32_e32 v75, 0xffff0000, v68
	v_lshlrev_b32_e32 v68, 16, v69
	v_and_b32_e32 v69, 0xffff0000, v69
	v_pk_add_f32 v[62:63], v[62:63], v[72:73]
	v_pk_add_f32 v[64:65], v[64:65], v[66:67]
	v_pk_add_f32 v[66:67], v[60:61], v[68:69]
	v_mul_f32_e32 v68, v63, v63
	v_fmac_f32_e32 v68, v62, v62
	v_fmac_f32_e32 v68, v64, v64
	v_pk_add_f32 v[60:61], v[58:59], v[74:75]
	v_fmac_f32_e32 v68, v65, v65
	v_fmac_f32_e32 v68, v60, v60
	v_cvt_pk_bf16_f32 v58, v62, v63
	v_add_u32_e32 v62, v76, v160
	v_fmac_f32_e32 v68, v61, v61
	v_cvt_pk_bf16_f32 v59, v64, v65
	v_cvt_pk_bf16_f32 v60, v60, v61
	v_cvt_pk_bf16_f32 v61, v66, v67
	buffer_store_dwordx4 v[58:61], v62, s[60:63], 0 offen sc1
	v_fmac_f32_e32 v68, v66, v66
	v_fmac_f32_e32 v68, v67, v67
	s_waitcnt vmcnt(15)
	v_mov_b32_e32 v58, v220
	v_mov_b32_e32 v59, v221
	v_mov_b32_e32 v60, v222
	v_mov_b32_e32 v61, v223
	v_lshlrev_b32_e32 v62, 16, v58
	v_and_b32_e32 v63, 0xffff0000, v58
	v_lshlrev_b32_e32 v58, 16, v59
	v_and_b32_e32 v59, 0xffff0000, v59
	v_lshlrev_b32_e32 v64, 16, v60
	v_and_b32_e32 v65, 0xffff0000, v60
	v_lshlrev_b32_e32 v60, 16, v61
	v_and_b32_e32 v61, 0xffff0000, v61
	v_pk_add_f32 v[54:55], v[54:55], v[62:63]
	v_pk_add_f32 v[56:57], v[56:57], v[58:59]
	v_pk_add_f32 v[58:59], v[52:53], v[60:61]
	v_pk_add_f32 v[52:53], v[50:51], v[64:65]
	v_mul_f32_e32 v50, v55, v55
	v_fmac_f32_e32 v50, v54, v54
	v_fmac_f32_e32 v50, v56, v56
	v_fmac_f32_e32 v50, v57, v57
	v_fmac_f32_e32 v50, v52, v52
	v_fmac_f32_e32 v50, v53, v53
	v_fmac_f32_e32 v50, v58, v58
	v_fmac_f32_e32 v50, v59, v59
	v_add_f32_e32 v60, v68, v50
	v_cvt_pk_bf16_f32 v50, v54, v55
	v_add_u32_e32 v54, v76, v116
	v_cvt_pk_bf16_f32 v51, v56, v57
	v_cvt_pk_bf16_f32 v52, v52, v53
	v_cvt_pk_bf16_f32 v53, v58, v59
	buffer_store_dwordx4 v[50:53], v54, s[60:63], 0 offen sc1
	ds_bpermute_b32 v50, v122, v60
	s_waitcnt lgkmcnt(0)
	v_add_f32_e32 v50, v60, v50
	ds_bpermute_b32 v51, v117, v50
	s_and_saveexec_b64 s[18:19], s[38:39]
	s_cbranch_execz .LBB0_851
	s_waitcnt lgkmcnt(0)
	v_add_f32_e32 v50, v50, v51
	v_mul_f32_e32 v50, 0x49800000, v50
	v_trunc_f32_e32 v50, v50
	v_mul_f32_e32 v51, 0x2f800000, v50
	v_floor_f32_e32 v51, v51
	v_fmac_f32_e32 v50, 0xcf800000, v51
	v_cvt_u32_f32_e32 v50, v50
	v_cvt_u32_f32_e32 v51, v51
	global_atomic_add_x2 v[114:115], v[50:51], off offset:1024
.LBB0_851:
	s_or_b64 exec, exec, s[18:19]
	v_add_u32_e32 v50, 0x90, v158
	s_waitcnt lgkmcnt(0)
	v_ashrrev_i32_e32 v51, 31, v50
	v_lshlrev_b64 v[50:51], 12, v[50:51]
	v_lshl_add_u64 v[54:55], v[156:157], 0, v[50:51]
	v_add_u32_e32 v60, 0x10800000, v50
	s_waitcnt vmcnt(15)
	v_mov_b32_e32 v50, v224
	v_mov_b32_e32 v51, v225
	v_mov_b32_e32 v52, v226
	v_mov_b32_e32 v53, v227
	v_lshlrev_b32_e32 v56, 16, v50
	v_and_b32_e32 v57, 0xffff0000, v50
	v_lshlrev_b32_e32 v50, 16, v51
	v_and_b32_e32 v51, 0xffff0000, v51
	v_lshlrev_b32_e32 v58, 16, v52
	v_and_b32_e32 v59, 0xffff0000, v52
	v_lshlrev_b32_e32 v52, 16, v53
	v_and_b32_e32 v53, 0xffff0000, v53
	v_pk_add_f32 v[46:47], v[46:47], v[56:57]
	v_pk_add_f32 v[48:49], v[48:49], v[50:51]
	v_pk_add_f32 v[50:51], v[44:45], v[52:53]
	v_mul_f32_e32 v52, v47, v47
	v_fmac_f32_e32 v52, v46, v46
	v_fmac_f32_e32 v52, v48, v48
	v_pk_add_f32 v[44:45], v[42:43], v[58:59]
	v_fmac_f32_e32 v52, v49, v49
	v_fmac_f32_e32 v52, v44, v44
	v_cvt_pk_bf16_f32 v42, v46, v47
	v_add_u32_e32 v46, v60, v160
	v_fmac_f32_e32 v52, v45, v45
	v_cvt_pk_bf16_f32 v43, v48, v49
	v_cvt_pk_bf16_f32 v44, v44, v45
	v_cvt_pk_bf16_f32 v45, v50, v51
	buffer_store_dwordx4 v[42:45], v46, s[60:63], 0 offen sc1
	v_fmac_f32_e32 v52, v50, v50
	v_fmac_f32_e32 v52, v51, v51
	s_waitcnt vmcnt(15)
	v_mov_b32_e32 v42, v228
	v_mov_b32_e32 v43, v229
	v_mov_b32_e32 v44, v230
	v_mov_b32_e32 v45, v231
	v_lshlrev_b32_e32 v46, 16, v42
	v_and_b32_e32 v47, 0xffff0000, v42
	v_lshlrev_b32_e32 v42, 16, v43
	v_and_b32_e32 v43, 0xffff0000, v43
	v_lshlrev_b32_e32 v48, 16, v44
	v_and_b32_e32 v49, 0xffff0000, v44
	v_lshlrev_b32_e32 v44, 16, v45
	v_and_b32_e32 v45, 0xffff0000, v45
	v_pk_add_f32 v[38:39], v[38:39], v[46:47]
	v_pk_add_f32 v[40:41], v[40:41], v[42:43]
	v_pk_add_f32 v[42:43], v[36:37], v[44:45]
	v_pk_add_f32 v[36:37], v[34:35], v[48:49]
	v_mul_f32_e32 v34, v39, v39
	v_fmac_f32_e32 v34, v38, v38
	v_fmac_f32_e32 v34, v40, v40
	v_fmac_f32_e32 v34, v41, v41
	v_fmac_f32_e32 v34, v36, v36
	v_fmac_f32_e32 v34, v37, v37
	v_fmac_f32_e32 v34, v42, v42
	v_fmac_f32_e32 v34, v43, v43
	v_add_f32_e32 v44, v52, v34
	v_cvt_pk_bf16_f32 v34, v38, v39
	v_add_u32_e32 v38, v60, v116
	v_cvt_pk_bf16_f32 v35, v40, v41
	v_cvt_pk_bf16_f32 v36, v36, v37
	v_cvt_pk_bf16_f32 v37, v42, v43
	buffer_store_dwordx4 v[34:37], v38, s[60:63], 0 offen sc1
	ds_bpermute_b32 v34, v122, v44
	s_waitcnt lgkmcnt(0)
	v_add_f32_e32 v34, v44, v34
	ds_bpermute_b32 v35, v117, v34
	s_and_saveexec_b64 s[18:19], s[38:39]
	s_cbranch_execz .LBB0_853
	s_waitcnt lgkmcnt(0)
	v_add_f32_e32 v34, v34, v35
	v_mul_f32_e32 v34, 0x49800000, v34
	v_trunc_f32_e32 v34, v34
	v_mul_f32_e32 v35, 0x2f800000, v34
	v_floor_f32_e32 v35, v35
	v_fmac_f32_e32 v34, 0xcf800000, v35
	v_cvt_u32_f32_e32 v34, v34
	v_cvt_u32_f32_e32 v35, v35
	global_atomic_add_x2 v[114:115], v[34:35], off offset:1152
; __device__ __forceinline__ unsigned cvt_pk_bf16(float lo, float hi) { unsigned r; asm("v_cvt_pk_bf16_f32 %0, %1, %2" : "=v"(r) : "v"(lo), "v"(hi)); return r; }
; __device__ __forceinline__ float bflo(unsigned w) { return __uint_as_float(w << 16); }
; __device__ __forceinline__ float bfhi(unsigned w) { return __uint_as_float(w & 0xffff0000u); }
; #define WT_STORE16(ptr, val) __builtin_amdgcn_raw_buffer_store_b128((val), wsr, (int)((const char*)(ptr) - (const char*)ws), 0, 16)
; template <int MODE>
; __device__ __forceinline__ void gemm_epilogue(const Params& p, int l, const f32x4 (&acc)[2][2][4][2], const Unit& u, int wr, int wc, int fr, int fq, const LAS float* rl, int pm0) {
;     ...
; #pragma unroll
;         for (int ai = 0; ai < 2; ++ai)
; #pragma unroll
;             for (int m = 0; m < 4; ++m) {
;                 const int tok = u.pm * 256 + 128 * ai + 64 * wr + 16 * m + fr;
;                 float part = 0.f;
; #pragma unroll
;                 for (int bj = 0; bj < 2; ++bj) {
;                     const size_t idx = (size_t)tok * 2048 + u.pn * 256 + 128 * bj + 32 * wc + 8 * fq;
;                     const u32x4 xw = *(const u32x4*)(xb + idx);
;                     f32x4 y0 = (f32x4){bflo(xw.x), bfhi(xw.x), bflo(xw.y), bfhi(xw.y)}, y1 = (f32x4){bflo(xw.z), bfhi(xw.z), bflo(xw.w), bfhi(xw.w)};
;                     y0 += acc[ai][bj][m][0]; y1 += acc[ai][bj][m][1];
;                     part += y0[0] * y0[0] + y0[1] * y0[1] + y0[2] * y0[2] + y0[3] * y0[3] + y1[0] * y1[0] + y1[1] * y1[1] + y1[2] * y1[2] + y1[3] * y1[3];
;                     u32x4 w; w.x = cvt_pk_bf16(y0[0], y0[1]); w.y = cvt_pk_bf16(y0[2], y0[3]); w.z = cvt_pk_bf16(y1[0], y1[1]); w.w = cvt_pk_bf16(y1[2], y1[3]);
;                     WT_STORE16(xb + idx, w);
;                 }
;                 part += __shfl_xor(part, 16); part += __shfl_xor(part, 32);
;                 if (fq == 0) atomicAdd(ssn + tok, (u64)(part * SS_SCALE));
;             }
.LBB0_853:
	s_or_b64 exec, exec, s[18:19]
	v_add_u32_e32 v34, 0xa0, v158
	s_waitcnt lgkmcnt(0)
	v_ashrrev_i32_e32 v35, 31, v34
	v_lshlrev_b64 v[34:35], 12, v[34:35]
	v_lshl_add_u64 v[38:39], v[156:157], 0, v[34:35]
	v_add_u32_e32 v44, 0x10800000, v34
	s_waitcnt vmcnt(14)
	v_mov_b32_e32 v34, v174
	v_mov_b32_e32 v35, v175
	v_mov_b32_e32 v36, v176
	v_mov_b32_e32 v37, v177
	v_lshlrev_b32_e32 v40, 16, v34
	v_and_b32_e32 v41, 0xffff0000, v34
	v_lshlrev_b32_e32 v34, 16, v35
	v_and_b32_e32 v35, 0xffff0000, v35
	v_lshlrev_b32_e32 v42, 16, v36
	v_and_b32_e32 v43, 0xffff0000, v36
	v_lshlrev_b32_e32 v36, 16, v37
	v_and_b32_e32 v37, 0xffff0000, v37
	v_pk_add_f32 v[30:31], v[30:31], v[40:41]
	v_pk_add_f32 v[32:33], v[32:33], v[34:35]
	v_pk_add_f32 v[34:35], v[28:29], v[36:37]
	v_mul_f32_e32 v36, v31, v31
	v_fmac_f32_e32 v36, v30, v30
	v_fmac_f32_e32 v36, v32, v32
	v_pk_add_f32 v[28:29], v[26:27], v[42:43]
	v_fmac_f32_e32 v36, v33, v33
	v_fmac_f32_e32 v36, v28, v28
	v_cvt_pk_bf16_f32 v26, v30, v31
	v_add_u32_e32 v30, v44, v160
	v_fmac_f32_e32 v36, v29, v29
	v_cvt_pk_bf16_f32 v27, v32, v33
	v_cvt_pk_bf16_f32 v28, v28, v29
	v_cvt_pk_bf16_f32 v29, v34, v35
	buffer_store_dwordx4 v[26:29], v30, s[60:63], 0 offen sc1
	v_fmac_f32_e32 v36, v34, v34
	v_fmac_f32_e32 v36, v35, v35
	s_waitcnt vmcnt(14)
	v_mov_b32_e32 v26, v178
	v_mov_b32_e32 v27, v179
	v_mov_b32_e32 v28, v180
	v_mov_b32_e32 v29, v181
	v_lshlrev_b32_e32 v30, 16, v26
	v_and_b32_e32 v31, 0xffff0000, v26
	v_lshlrev_b32_e32 v26, 16, v27
	v_and_b32_e32 v27, 0xffff0000, v27
	v_lshlrev_b32_e32 v32, 16, v28
	v_and_b32_e32 v33, 0xffff0000, v28
	v_lshlrev_b32_e32 v28, 16, v29
	v_and_b32_e32 v29, 0xffff0000, v29
	v_pk_add_f32 v[22:23], v[22:23], v[30:31]
	v_pk_add_f32 v[24:25], v[24:25], v[26:27]
	v_pk_add_f32 v[26:27], v[20:21], v[28:29]
	v_pk_add_f32 v[20:21], v[18:19], v[32:33]
	v_mul_f32_e32 v18, v23, v23
	v_fmac_f32_e32 v18, v22, v22
	v_fmac_f32_e32 v18, v24, v24
	v_fmac_f32_e32 v18, v25, v25
	v_fmac_f32_e32 v18, v20, v20
	v_fmac_f32_e32 v18, v21, v21
	v_fmac_f32_e32 v18, v26, v26
	v_fmac_f32_e32 v18, v27, v27
	v_add_f32_e32 v28, v36, v18
	v_cvt_pk_bf16_f32 v18, v22, v23
	v_add_u32_e32 v22, v44, v116
	v_cvt_pk_bf16_f32 v19, v24, v25
	v_cvt_pk_bf16_f32 v20, v20, v21
	v_cvt_pk_bf16_f32 v21, v26, v27
	buffer_store_dwordx4 v[18:21], v22, s[60:63], 0 offen sc1
	ds_bpermute_b32 v18, v122, v28
	s_waitcnt lgkmcnt(0)
	v_add_f32_e32 v18, v28, v18
	ds_bpermute_b32 v19, v117, v18
	s_and_saveexec_b64 s[18:19], s[38:39]
	s_cbranch_execz .LBB0_855
	s_waitcnt lgkmcnt(0)
	v_add_f32_e32 v18, v18, v19
	v_mul_f32_e32 v18, 0x49800000, v18
	v_trunc_f32_e32 v18, v18
	v_mul_f32_e32 v19, 0x2f800000, v18
	v_floor_f32_e32 v19, v19
	v_fmac_f32_e32 v18, 0xcf800000, v19
	v_cvt_u32_f32_e32 v18, v18
	v_cvt_u32_f32_e32 v19, v19
	global_atomic_add_x2 v[114:115], v[18:19], off offset:1280
.LBB0_855:
	s_or_b64 exec, exec, s[18:19]
	v_add_u32_e32 v18, 0xb0, v158
	s_waitcnt lgkmcnt(0)
	v_ashrrev_i32_e32 v19, 31, v18
	v_lshlrev_b64 v[22:23], 12, v[18:19]
	v_lshl_add_u64 v[24:25], v[156:157], 0, v[22:23]
	v_add_u32_e32 v28, 0x10800000, v22
	v_add_u32_e32 v29, v28, v160
	s_waitcnt vmcnt(12)
	v_mov_b32_e32 v18, v182
	v_mov_b32_e32 v19, v183
	v_mov_b32_e32 v20, v184
	v_mov_b32_e32 v21, v185
	v_lshlrev_b32_e32 v22, 16, v18
	v_and_b32_e32 v23, 0xffff0000, v18
	v_lshlrev_b32_e32 v18, 16, v19
	v_and_b32_e32 v19, 0xffff0000, v19
	v_lshlrev_b32_e32 v26, 16, v20
	v_and_b32_e32 v27, 0xffff0000, v20
	v_lshlrev_b32_e32 v20, 16, v21
	v_and_b32_e32 v21, 0xffff0000, v21
	v_pk_add_f32 v[16:17], v[16:17], v[18:19]
	v_pk_add_f32 v[14:15], v[14:15], v[22:23]
	v_pk_add_f32 v[18:19], v[12:13], v[20:21]
	v_pk_add_f32 v[20:21], v[10:11], v[26:27]
	v_cvt_pk_bf16_f32 v10, v14, v15
	v_cvt_pk_bf16_f32 v11, v16, v17
	v_cvt_pk_bf16_f32 v13, v18, v19
	v_mul_f32_e32 v22, v15, v15
	v_cvt_pk_bf16_f32 v12, v20, v21
	buffer_store_dwordx4 v[10:13], v29, s[60:63], 0 offen sc1
	v_fmac_f32_e32 v22, v14, v14
	v_fmac_f32_e32 v22, v16, v16
	v_fmac_f32_e32 v22, v17, v17
	v_fmac_f32_e32 v22, v20, v20
	v_fmac_f32_e32 v22, v21, v21
	v_fmac_f32_e32 v22, v18, v18
	v_fmac_f32_e32 v22, v19, v19
	s_waitcnt vmcnt(12)
	v_mov_b32_e32 v10, v186
	v_mov_b32_e32 v11, v187
	v_mov_b32_e32 v12, v188
	v_mov_b32_e32 v13, v189
	v_lshlrev_b32_e32 v14, 16, v10
	v_and_b32_e32 v15, 0xffff0000, v10
	v_lshlrev_b32_e32 v10, 16, v11
	v_and_b32_e32 v11, 0xffff0000, v11
	v_lshlrev_b32_e32 v16, 16, v12
	v_and_b32_e32 v17, 0xffff0000, v12
	v_lshlrev_b32_e32 v12, 16, v13
	v_and_b32_e32 v13, 0xffff0000, v13
	v_pk_add_f32 v[6:7], v[6:7], v[14:15]
	v_pk_add_f32 v[8:9], v[8:9], v[10:11]
	v_pk_add_f32 v[10:11], v[4:5], v[12:13]
	v_pk_add_f32 v[12:13], v[2:3], v[16:17]
	v_mul_f32_e32 v2, v7, v7
	v_fmac_f32_e32 v2, v6, v6
	v_fmac_f32_e32 v2, v8, v8
	v_fmac_f32_e32 v2, v9, v9
	v_fmac_f32_e32 v2, v12, v12
	v_fmac_f32_e32 v2, v13, v13
	v_fmac_f32_e32 v2, v10, v10
	v_fmac_f32_e32 v2, v11, v11
	v_add_f32_e32 v2, v22, v2
	ds_bpermute_b32 v3, v122, v2
	v_cvt_pk_bf16_f32 v5, v8, v9
	v_add_u32_e32 v8, v28, v116
	v_cvt_pk_bf16_f32 v4, v6, v7
	v_cvt_pk_bf16_f32 v6, v12, v13
	s_waitcnt lgkmcnt(0)
	v_add_f32_e32 v2, v2, v3
	ds_bpermute_b32 v3, v117, v2
	v_cvt_pk_bf16_f32 v7, v10, v11
	buffer_store_dwordx4 v[4:7], v8, s[60:63], 0 offen sc1
	s_and_saveexec_b64 s[18:19], s[38:39]
	s_cbranch_execz .LBB0_836
	s_waitcnt lgkmcnt(0)
	v_add_f32_e32 v2, v2, v3
	v_mul_f32_e32 v2, 0x49800000, v2
	v_trunc_f32_e32 v2, v2
	v_mul_f32_e32 v3, 0x2f800000, v2
	v_floor_f32_e32 v3, v3
	v_fmac_f32_e32 v2, 0xcf800000, v3
	v_cvt_u32_f32_e32 v2, v2
	v_cvt_u32_f32_e32 v3, v3
	global_atomic_add_x2 v[114:115], v[2:3], off offset:1408
	s_branch .LBB0_836
